# v21 + P8 epilogue gate loads hoisted above the second K-loop's end and mid-K gate loads issued as a rolling prefetch (amplified 5x-P8 probe showed -13 us per P8 pass)
# speedup vs baseline: 1.0032x; 1.0020x over previous
; #define PG8_STAGE(bufoff, gbase, voff) do { _Pragma("unroll") for (int _i = 0; _i < 2; ++_i) \
;         __builtin_amdgcn_global_load_lds((const unsigned*)((const char*)(gbase) + (voff)[_i]), (PG8_LAS unsigned*)(lds + (bufoff) + ldsw + _i * 8192), 16, 0, 0); } while (0)
; #define PG8_LDA(dst, b, h) do { _Pragma("unroll") for (int m = 0; m < 4; ++m) _Pragma("unroll") for (int k = 0; k < 2; ++k) dst[m][k] = *(const PG8_LAS bf16x8*)(lds + PG8_SA(b, h) + aoff + m * 2048 + k * 1024); } while (0)
; #define PG8_LDB(dst, b, h) do { _Pragma("unroll") for (int n = 0; n < 2; ++n) _Pragma("unroll") for (int k = 0; k < 2; ++k) dst[n][k] = *(const PG8_LAS bf16x8*)(lds + PG8_SB(b, h) + boff + n * 2048 + k * 1024); } while (0)
; template <class Epi, class Sched, bool ALIGN_EPI = false, bool SP2 = false>
; __device__ __forceinline__ void gemm_phase(PG8_LAS unsigned char* lds, const Gemm g, const Sched& S, const Epi& E) {
;     ...
;         for (; t < tend; t += 2) {
;             const bool last = (t == nt - 2);
;             const char* a1 = cA + (size_t)(t + 1) * kstep;
;             const char* a2 = last ? nA : cA + (size_t)(t + 2) * kstep; const char* b2 = last ? nB : cB + (size_t)(t + 2) * kstep;
;             const char* a3 = a2 + kstep; const char* b3 = b2 + kstep;
;             if (last && has_next) S.a_ready(nxt);
;             if constexpr (SP2) {
;             PG8_LDB(B0, 0, 0); PG8_LDB(B1, 0, 1); PG8_SCHED; PG8_LDA(At, 0, 0); PG8_STAGE(PG8_SA(1, 1), a1 + hstep, voffA);
;             PG8_WAIT_V(8); PG8_WAIT_L(0); PG8_BAR; PG8_MMA(0, 0, At, B0); PG8_MMA(0, 1, At, B1); PG8_BAR; PG8_SCHED;
;             PG8_LDA(At, 0, 1); PG8_STAGE(PG8_SB(0, 0), b2, voffB); PG8_STAGE(PG8_SB(0, 1), b2 + hstep, voffB); PG8_STAGE(PG8_SA(0, 0), a2, voffA);
;             PG8_WAIT_V(8); PG8_WAIT_L(0); PG8_BAR; PG8_MMA(1, 0, At, B0); PG8_MMA(1, 1, At, B1); PG8_BAR; PG8_SCHED;
;             PG8_LDB(B0, 1, 0); PG8_LDB(B1, 1, 1); PG8_SCHED; PG8_LDA(At, 1, 0); PG8_STAGE(PG8_SA(0, 1), a2 + hstep, voffA);
;             PG8_WAIT_V(8); PG8_WAIT_L(0); PG8_BAR; PG8_MMA(0, 0, At, B0); PG8_MMA(0, 1, At, B1); PG8_BAR; PG8_SCHED;
;             PG8_LDA(At, 1, 1); PG8_STAGE(PG8_SB(1, 0), b3, voffB); PG8_STAGE(PG8_SB(1, 1), b3 + hstep, voffB); PG8_STAGE(PG8_SA(1, 0), a3, voffA);
;             PG8_WAIT_V(8); PG8_WAIT_L(0); PG8_BAR; PG8_MMA(1, 0, At, B0); PG8_MMA(1, 1, At, B1); PG8_BAR; PG8_SCHED;
.LBB0_682:
	ds_read_b128 v[166:169], v163
	ds_read_b128 v[170:173], v163 offset:1024
	ds_read_b128 v[174:177], v163 offset:2048
	ds_read_b128 v[180:183], v163 offset:3072
	ds_read_b128 v[184:187], v164
	ds_read_b128 v[188:191], v164 offset:1024
	ds_read_b128 v[198:201], v164 offset:2048
	ds_read_b128 v[202:205], v164 offset:3072
	v_lshl_add_u64 v[242:243], v[130:131], 0, s[44:45]
	s_add_i32 s83, s29, 0xc000
	v_lshl_add_u64 v[238:239], v[242:243], 0, s[10:11]
	s_mov_b32 m0, s83
	v_lshl_add_u64 v[244:245], v[132:133], 0, s[44:45]
	s_add_i32 s84, s29, 0xe000
	ds_read_b128 v[206:209], v165
	ds_read_b128 v[210:213], v165 offset:1024
	ds_read_b128 v[214:217], v165 offset:2048
	ds_read_b128 v[218:221], v165 offset:3072
	ds_read_b128 v[222:225], v165 offset:4096
	ds_read_b128 v[226:229], v165 offset:5120
	ds_read_b128 v[230:233], v165 offset:6144
	ds_read_b128 v[234:237], v165 offset:7168
	global_load_lds_dwordx4 v[238:239], off
	v_lshl_add_u64 v[238:239], v[244:245], 0, s[10:11]
	s_mov_b32 m0, s84
	s_nop 0
	global_load_lds_dwordx4 v[238:239], off
	s_waitcnt vmcnt(8)
	s_waitcnt lgkmcnt(0)
	s_barrier
	s_waitcnt lgkmcnt(0)
	v_mfma_f32_16x16x32_bf16 v[14:17], v[166:169], v[206:209], v[14:17]
	v_mfma_f32_16x16x32_bf16 v[14:17], v[170:173], v[210:213], v[14:17]
	v_mfma_f32_16x16x32_bf16 v[38:41], v[170:173], v[218:221], v[38:41]
	v_mfma_f32_16x16x32_bf16 v[38:41], v[166:169], v[214:217], v[38:41]
	v_mfma_f32_16x16x32_bf16 v[70:73], v[166:169], v[222:225], v[70:73]
	v_mfma_f32_16x16x32_bf16 v[70:73], v[170:173], v[226:229], v[70:73]
	v_mfma_f32_16x16x32_bf16 v[94:97], v[170:173], v[234:237], v[94:97]
	v_mfma_f32_16x16x32_bf16 v[94:97], v[166:169], v[230:233], v[94:97]
	v_mfma_f32_16x16x32_bf16 v[90:93], v[174:177], v[230:233], v[90:93]
	v_mfma_f32_16x16x32_bf16 v[90:93], v[180:183], v[234:237], v[90:93]
	v_mfma_f32_16x16x32_bf16 v[66:69], v[180:183], v[226:229], v[66:69]
	v_mfma_f32_16x16x32_bf16 v[66:69], v[174:177], v[222:225], v[66:69]
	v_mfma_f32_16x16x32_bf16 v[34:37], v[174:177], v[214:217], v[34:37]
	v_mfma_f32_16x16x32_bf16 v[34:37], v[180:183], v[218:221], v[34:37]
	v_mfma_f32_16x16x32_bf16 v[10:13], v[180:183], v[210:213], v[10:13]
	v_mfma_f32_16x16x32_bf16 v[10:13], v[174:177], v[206:209], v[10:13]
	v_mfma_f32_16x16x32_bf16 v[30:33], v[184:187], v[206:209], v[30:33]
	v_mfma_f32_16x16x32_bf16 v[30:33], v[188:191], v[210:213], v[30:33]
	v_mfma_f32_16x16x32_bf16 v[54:57], v[188:191], v[218:221], v[54:57]
	v_mfma_f32_16x16x32_bf16 v[54:57], v[184:187], v[214:217], v[54:57]
	v_mfma_f32_16x16x32_bf16 v[86:89], v[184:187], v[222:225], v[86:89]
	v_mfma_f32_16x16x32_bf16 v[86:89], v[188:191], v[226:229], v[86:89]
	v_mfma_f32_16x16x32_bf16 v[110:113], v[188:191], v[234:237], v[110:113]
	v_mfma_f32_16x16x32_bf16 v[110:113], v[184:187], v[230:233], v[110:113]
	v_mfma_f32_16x16x32_bf16 v[106:109], v[198:201], v[230:233], v[106:109]
	v_mfma_f32_16x16x32_bf16 v[106:109], v[202:205], v[234:237], v[106:109]
	v_mfma_f32_16x16x32_bf16 v[82:85], v[202:205], v[226:229], v[82:85]
	v_mfma_f32_16x16x32_bf16 v[82:85], v[198:201], v[222:225], v[82:85]
	v_mfma_f32_16x16x32_bf16 v[50:53], v[198:201], v[214:217], v[50:53]
	v_mfma_f32_16x16x32_bf16 v[50:53], v[202:205], v[218:221], v[50:53]
	v_mfma_f32_16x16x32_bf16 v[26:29], v[202:205], v[210:213], v[26:29]
	v_mfma_f32_16x16x32_bf16 v[26:29], v[198:201], v[206:209], v[26:29]
	s_barrier
	v_lshl_add_u64 v[246:247], v[156:157], 0, s[44:45]
	s_add_i32 s85, s80, s28
	v_lshl_add_u64 v[238:239], v[246:247], 0, s[14:15]
	s_mov_b32 m0, s85
	v_lshl_add_u64 v[248:249], v[158:159], 0, s[44:45]
	s_add_i32 s86, s85, 0x2000
	ds_read_b128 v[206:209], v165 offset:16384
	ds_read_b128 v[210:213], v165 offset:17408
	ds_read_b128 v[214:217], v165 offset:18432
	ds_read_b128 v[218:221], v165 offset:19456
	ds_read_b128 v[222:225], v165 offset:20480
	ds_read_b128 v[226:229], v165 offset:21504
	ds_read_b128 v[230:233], v165 offset:22528
	ds_read_b128 v[234:237], v165 offset:23552
	global_load_lds_dwordx4 v[238:239], off
	v_lshl_add_u64 v[238:239], v[248:249], 0, s[14:15]
	s_mov_b32 m0, s86
	s_add_i32 s87, s81, s28
	global_load_lds_dwordx4 v[238:239], off
	v_lshl_add_u64 v[238:239], v[246:247], 0, s[16:17]
	s_mov_b32 m0, s87
	s_add_i32 s88, s87, 0x2000
	global_load_lds_dwordx4 v[238:239], off
	v_lshl_add_u64 v[238:239], v[248:249], 0, s[16:17]
	s_mov_b32 m0, s88
	s_nop 0
	global_load_lds_dwordx4 v[238:239], off
	v_lshl_add_u64 v[238:239], v[242:243], 0, s[14:15]
	s_mov_b32 m0, s29
	s_nop 0
	global_load_lds_dwordx4 v[238:239], off
	v_lshl_add_u64 v[238:239], v[244:245], 0, s[14:15]
	s_mov_b32 m0, s30
	s_nop 0
	global_load_lds_dwordx4 v[238:239], off
	s_waitcnt vmcnt(8)
	s_waitcnt lgkmcnt(0)
	s_barrier
; #define PG8_STAGE(bufoff, gbase, voff) do { _Pragma("unroll") for (int _i = 0; _i < 2; ++_i) \
;         __builtin_amdgcn_global_load_lds((const unsigned*)((const char*)(gbase) + (voff)[_i]), (PG8_LAS unsigned*)(lds + (bufoff) + ldsw + _i * 8192), 16, 0, 0); } while (0)
; #define PG8_LDA(dst, b, h) do { _Pragma("unroll") for (int m = 0; m < 4; ++m) _Pragma("unroll") for (int k = 0; k < 2; ++k) dst[m][k] = *(const PG8_LAS bf16x8*)(lds + PG8_SA(b, h) + aoff + m * 2048 + k * 1024); } while (0)
; #define PG8_LDB(dst, b, h) do { _Pragma("unroll") for (int n = 0; n < 2; ++n) _Pragma("unroll") for (int k = 0; k < 2; ++k) dst[n][k] = *(const PG8_LAS bf16x8*)(lds + PG8_SB(b, h) + boff + n * 2048 + k * 1024); } while (0)
; #define PG8_MMA(ai, bj, At, Bt) do { __builtin_amdgcn_s_setprio(1); _Pragma("unroll") for (int m = 0; m < 4; ++m) _Pragma("unroll") for (int n = 0; n < 2; ++n) _Pragma("unroll") for (int k = 0; k < 2; ++k) \
;         acc[ai][bj][m][n] = __builtin_amdgcn_mfma_f32_16x16x32_bf16(Bt[n][k], At[m][k], acc[ai][bj][m][n], 0, 0, 0); __builtin_amdgcn_s_setprio(0); } while (0)
; #define PG8_WAIT_V(n) asm volatile("s_waitcnt vmcnt(" #n ")" ::: "memory")
; #define PG8_WAIT_L(n) asm volatile("s_waitcnt lgkmcnt(" #n ")" ::: "memory")
; #define PG8_BAR __builtin_amdgcn_s_barrier()
; #define PG8_SCHED __builtin_amdgcn_sched_barrier(0)
; template <class Epi, class Sched, bool ALIGN_EPI = false, bool SP2 = false>
; __device__ __forceinline__ void gemm_phase(PG8_LAS unsigned char* lds, const Gemm g, const Sched& S, const Epi& E) {
;     ...
;             PG8_WAIT_V(8); PG8_WAIT_L(0); PG8_BAR; PG8_MMA(1, 0, At, B0); PG8_MMA(1, 1, At, B1); PG8_BAR; PG8_SCHED;
;             PG8_LDB(B0, 1, 0); PG8_LDB(B1, 1, 1); PG8_SCHED; PG8_LDA(At, 1, 0); PG8_STAGE(PG8_SA(0, 1), a2 + hstep, voffA);
;             PG8_WAIT_V(8); PG8_WAIT_L(0); PG8_BAR; PG8_MMA(0, 0, At, B0); PG8_MMA(0, 1, At, B1); PG8_BAR; PG8_SCHED;
	s_waitcnt lgkmcnt(0)
	v_mfma_f32_16x16x32_bf16 v[126:129], v[166:169], v[206:209], v[126:129]
	v_mfma_f32_16x16x32_bf16 v[126:129], v[170:173], v[210:213], v[126:129]
	v_mfma_f32_16x16x32_bf16 v[102:105], v[170:173], v[218:221], v[102:105]
	v_mfma_f32_16x16x32_bf16 v[102:105], v[166:169], v[214:217], v[102:105]
	v_mfma_f32_16x16x32_bf16 v[62:65], v[166:169], v[222:225], v[62:65]
	v_mfma_f32_16x16x32_bf16 v[62:65], v[170:173], v[226:229], v[62:65]
	v_mfma_f32_16x16x32_bf16 v[22:25], v[170:173], v[234:237], v[22:25]
	v_mfma_f32_16x16x32_bf16 v[22:25], v[166:169], v[230:233], v[22:25]
	v_mfma_f32_16x16x32_bf16 v[18:21], v[174:177], v[230:233], v[18:21]
	v_mfma_f32_16x16x32_bf16 v[18:21], v[180:183], v[234:237], v[18:21]
	v_mfma_f32_16x16x32_bf16 v[58:61], v[180:183], v[226:229], v[58:61]
	v_mfma_f32_16x16x32_bf16 v[58:61], v[174:177], v[222:225], v[58:61]
	v_mfma_f32_16x16x32_bf16 v[98:101], v[174:177], v[214:217], v[98:101]
	v_mfma_f32_16x16x32_bf16 v[98:101], v[180:183], v[218:221], v[98:101]
	v_mfma_f32_16x16x32_bf16 v[122:125], v[180:183], v[210:213], v[122:125]
	v_mfma_f32_16x16x32_bf16 v[122:125], v[174:177], v[206:209], v[122:125]
	v_mfma_f32_16x16x32_bf16 v[118:121], v[184:187], v[206:209], v[118:121]
	v_mfma_f32_16x16x32_bf16 v[118:121], v[188:191], v[210:213], v[118:121]
	v_mfma_f32_16x16x32_bf16 v[78:81], v[188:191], v[218:221], v[78:81]
	v_mfma_f32_16x16x32_bf16 v[78:81], v[184:187], v[214:217], v[78:81]
	v_mfma_f32_16x16x32_bf16 v[46:49], v[184:187], v[222:225], v[46:49]
	v_mfma_f32_16x16x32_bf16 v[46:49], v[188:191], v[226:229], v[46:49]
	v_mfma_f32_16x16x32_bf16 v[6:9], v[188:191], v[234:237], v[6:9]
	v_mfma_f32_16x16x32_bf16 v[6:9], v[184:187], v[230:233], v[6:9]
	v_mfma_f32_16x16x32_bf16 v[2:5], v[198:201], v[230:233], v[2:5]
	v_mfma_f32_16x16x32_bf16 v[2:5], v[202:205], v[234:237], v[2:5]
	v_mfma_f32_16x16x32_bf16 v[42:45], v[202:205], v[226:229], v[42:45]
	v_mfma_f32_16x16x32_bf16 v[42:45], v[198:201], v[222:225], v[42:45]
	v_mfma_f32_16x16x32_bf16 v[74:77], v[198:201], v[214:217], v[74:77]
	v_mfma_f32_16x16x32_bf16 v[74:77], v[202:205], v[218:221], v[74:77]
	v_mfma_f32_16x16x32_bf16 v[114:117], v[202:205], v[210:213], v[114:117]
	v_mfma_f32_16x16x32_bf16 v[114:117], v[198:201], v[206:209], v[114:117]
	s_barrier
	s_add_i32 s89, 0, 0x18000
	s_add_i32 s91, 0, 0x1c000
	v_add_u32_e32 v142, s89, v161
	v_add_u32_e32 v167, s91, v161
	ds_read_b128 v[168:171], v142
	ds_read_b128 v[172:175], v142 offset:1024
	ds_read_b128 v[180:183], v142 offset:2048
	ds_read_b128 v[184:187], v142 offset:3072
	ds_read_b128 v[188:191], v167
	ds_read_b128 v[198:201], v167 offset:1024
	ds_read_b128 v[202:205], v167 offset:2048
	ds_read_b128 v[206:209], v167 offset:3072
	s_mov_b32 m0, s31
	v_lshl_add_u64 v[176:177], v[242:243], 0, s[16:17]
	ds_read_b128 v[210:213], v165 offset:32768
	ds_read_b128 v[214:217], v165 offset:33792
	ds_read_b128 v[218:221], v165 offset:34816
	ds_read_b128 v[222:225], v165 offset:35840
	ds_read_b128 v[226:229], v165 offset:36864
	ds_read_b128 v[230:233], v165 offset:37888
	ds_read_b128 v[234:237], v165 offset:38912
	ds_read_b128 v[238:241], v165 offset:39936
	global_load_lds_dwordx4 v[176:177], off
	v_lshl_add_u64 v[176:177], v[244:245], 0, s[16:17]
	s_mov_b32 m0, s35
	s_nop 0
	global_load_lds_dwordx4 v[176:177], off
	s_waitcnt vmcnt(8)
	s_waitcnt lgkmcnt(0)
	s_barrier
	s_waitcnt lgkmcnt(0)
	v_mfma_f32_16x16x32_bf16 v[14:17], v[168:171], v[210:213], v[14:17]
	v_mfma_f32_16x16x32_bf16 v[14:17], v[172:175], v[214:217], v[14:17]
	v_mfma_f32_16x16x32_bf16 v[38:41], v[172:175], v[222:225], v[38:41]
	v_mfma_f32_16x16x32_bf16 v[38:41], v[168:171], v[218:221], v[38:41]
	v_mfma_f32_16x16x32_bf16 v[70:73], v[168:171], v[226:229], v[70:73]
	v_mfma_f32_16x16x32_bf16 v[70:73], v[172:175], v[230:233], v[70:73]
	v_mfma_f32_16x16x32_bf16 v[94:97], v[172:175], v[238:241], v[94:97]
	v_mfma_f32_16x16x32_bf16 v[94:97], v[168:171], v[234:237], v[94:97]
	v_mfma_f32_16x16x32_bf16 v[90:93], v[180:183], v[234:237], v[90:93]
	v_mfma_f32_16x16x32_bf16 v[90:93], v[184:187], v[238:241], v[90:93]
	v_mfma_f32_16x16x32_bf16 v[66:69], v[184:187], v[230:233], v[66:69]
	v_mfma_f32_16x16x32_bf16 v[66:69], v[180:183], v[226:229], v[66:69]
	v_mfma_f32_16x16x32_bf16 v[34:37], v[180:183], v[218:221], v[34:37]
	v_mfma_f32_16x16x32_bf16 v[34:37], v[184:187], v[222:225], v[34:37]
	v_mfma_f32_16x16x32_bf16 v[10:13], v[184:187], v[214:217], v[10:13]
	v_mfma_f32_16x16x32_bf16 v[10:13], v[180:183], v[210:213], v[10:13]
	v_mfma_f32_16x16x32_bf16 v[30:33], v[188:191], v[210:213], v[30:33]
	v_mfma_f32_16x16x32_bf16 v[30:33], v[198:201], v[214:217], v[30:33]
	v_mfma_f32_16x16x32_bf16 v[54:57], v[198:201], v[222:225], v[54:57]
	v_mfma_f32_16x16x32_bf16 v[54:57], v[188:191], v[218:221], v[54:57]
	v_mfma_f32_16x16x32_bf16 v[86:89], v[188:191], v[226:229], v[86:89]
	v_mfma_f32_16x16x32_bf16 v[86:89], v[198:201], v[230:233], v[86:89]
	v_mfma_f32_16x16x32_bf16 v[110:113], v[198:201], v[238:241], v[110:113]
	v_mfma_f32_16x16x32_bf16 v[110:113], v[188:191], v[234:237], v[110:113]
	v_mfma_f32_16x16x32_bf16 v[106:109], v[202:205], v[234:237], v[106:109]
	v_mfma_f32_16x16x32_bf16 v[106:109], v[206:209], v[238:241], v[106:109]
	v_mfma_f32_16x16x32_bf16 v[82:85], v[206:209], v[230:233], v[82:85]
	v_mfma_f32_16x16x32_bf16 v[82:85], v[202:205], v[226:229], v[82:85]
	v_mfma_f32_16x16x32_bf16 v[50:53], v[202:205], v[218:221], v[50:53]
	v_mfma_f32_16x16x32_bf16 v[50:53], v[206:209], v[222:225], v[50:53]
	v_mfma_f32_16x16x32_bf16 v[26:29], v[206:209], v[214:217], v[26:29]
	v_mfma_f32_16x16x32_bf16 v[26:29], v[202:205], v[210:213], v[26:29]
	s_barrier
; #define PG8_WAIT_V(n) asm volatile("s_waitcnt vmcnt(" #n ")" ::: "memory")
;     __device__ __forceinline__ void mid(f32x4 (&acc)[2][2][4][2], const Unit& u, int wr, int wc, int fr, int fq) const {
;         int row0 = u.pm * BM + wr * 64 + fr; const int col0 = u.pn * BM + wc * 32 + 8 * fq;
;         asm volatile("" : "+v"(row0));
; #pragma unroll
;         for (int ai = 0; ai < 2; ++ai)
; #pragma unroll
;             for (int m = 0; m < 4; ++m) { const bf16_t* pr = P + (size_t)(row0 + ai * HALF + m * 16) * NP + col0;
; #pragma unroll
;                 for (int bj = 0; bj < 2; ++bj) { const u32x4 a = *(const u32x4*)(pr + PC_GA + bj * HALF), b = *(const u32x4*)(pr + PC_GB + bj * HALF);
; template <class Epi, class Sched, bool ALIGN_EPI = false, bool SP2 = false>
; __device__ __forceinline__ void gemm_phase(PG8_LAS unsigned char* lds, const Gemm g, const Sched& S, const Epi& E) {
;     ...
;         for (; t < tend; t += 2) {
;             const bool last = (t == nt - 2);
;             const char* a1 = cA + (size_t)(t + 1) * kstep;
;             const char* a2 = last ? nA : cA + (size_t)(t + 2) * kstep; const char* b2 = last ? nB : cB + (size_t)(t + 2) * kstep;
;             const char* a3 = a2 + kstep; const char* b3 = b2 + kstep;
;             if (last && has_next) S.a_ready(nxt);
;             if constexpr (SP2) {
;             PG8_LDB(B0, 0, 0); PG8_LDB(B1, 0, 1); PG8_SCHED; PG8_LDA(At, 0, 0); PG8_STAGE(PG8_SA(1, 1), a1 + hstep, voffA);
;             PG8_WAIT_V(8); PG8_WAIT_L(0); PG8_BAR; PG8_MMA(0, 0, At, B0); PG8_MMA(0, 1, At, B1); PG8_BAR; PG8_SCHED;
;             PG8_LDA(At, 0, 1); PG8_STAGE(PG8_SB(0, 0), b2, voffB); PG8_STAGE(PG8_SB(0, 1), b2 + hstep, voffB); PG8_STAGE(PG8_SA(0, 0), a2, voffA);
;             PG8_WAIT_V(8); PG8_WAIT_L(0); PG8_BAR; PG8_MMA(1, 0, At, B0); PG8_MMA(1, 1, At, B1); PG8_BAR; PG8_SCHED;
;             PG8_LDB(B0, 1, 0); PG8_LDB(B1, 1, 1); PG8_SCHED; PG8_LDA(At, 1, 0); PG8_STAGE(PG8_SA(0, 1), a2 + hstep, voffA);
;             PG8_WAIT_V(8); PG8_WAIT_L(0); PG8_BAR; PG8_MMA(0, 0, At, B0); PG8_MMA(0, 1, At, B1); PG8_BAR; PG8_SCHED;
;             PG8_LDA(At, 1, 1); PG8_STAGE(PG8_SB(1, 0), b3, voffB); PG8_STAGE(PG8_SB(1, 1), b3 + hstep, voffB); PG8_STAGE(PG8_SA(1, 0), a3, voffA);
;             PG8_WAIT_V(8); PG8_WAIT_L(0); PG8_BAR; PG8_MMA(1, 0, At, B0); PG8_MMA(1, 1, At, B1); PG8_BAR; PG8_SCHED;
	s_add_i32 s89, s89, s28
	v_lshl_add_u64 v[176:177], v[246:247], 0, s[22:23]
	s_mov_b32 m0, s89
	s_add_i32 s90, s89, 0x2000
	ds_read_b128 v[210:213], v165 offset:49152
	ds_read_b128 v[214:217], v165 offset:50176
	ds_read_b128 v[218:221], v165 offset:51200
	ds_read_b128 v[222:225], v165 offset:52224
	ds_read_b128 v[226:229], v165 offset:53248
	ds_read_b128 v[230:233], v165 offset:54272
	ds_read_b128 v[234:237], v165 offset:55296
	ds_read_b128 v[238:241], v165 offset:56320
	global_load_lds_dwordx4 v[176:177], off
	v_lshl_add_u64 v[176:177], v[248:249], 0, s[22:23]
	s_mov_b32 m0, s90
	s_add_i32 s91, s91, s28
	global_load_lds_dwordx4 v[176:177], off
	v_lshl_add_u64 v[176:177], v[246:247], 0, s[36:37]
	s_mov_b32 m0, s91
	s_add_i32 s92, s91, 0x2000
	global_load_lds_dwordx4 v[176:177], off
	v_lshl_add_u64 v[176:177], v[248:249], 0, s[36:37]
	s_mov_b32 m0, s92
	s_nop 0
	global_load_lds_dwordx4 v[176:177], off
	v_lshl_add_u64 v[176:177], v[242:243], 0, s[22:23]
	s_mov_b32 m0, s75
	s_nop 0
	global_load_lds_dwordx4 v[176:177], off
	v_lshl_add_u64 v[176:177], v[244:245], 0, s[22:23]
	s_mov_b32 m0, s76
	s_nop 0
	global_load_lds_dwordx4 v[176:177], off
	s_waitcnt vmcnt(8)
	s_waitcnt lgkmcnt(0)
	s_barrier
	s_waitcnt lgkmcnt(0)
	v_mfma_f32_16x16x32_bf16 v[126:129], v[168:171], v[210:213], v[126:129]
	v_mfma_f32_16x16x32_bf16 v[126:129], v[172:175], v[214:217], v[126:129]
	v_mfma_f32_16x16x32_bf16 v[102:105], v[172:175], v[222:225], v[102:105]
	v_mfma_f32_16x16x32_bf16 v[102:105], v[168:171], v[218:221], v[102:105]
	v_mfma_f32_16x16x32_bf16 v[62:65], v[168:171], v[226:229], v[62:65]
	v_mfma_f32_16x16x32_bf16 v[62:65], v[172:175], v[230:233], v[62:65]
	v_mfma_f32_16x16x32_bf16 v[22:25], v[172:175], v[238:241], v[22:25]
	v_mfma_f32_16x16x32_bf16 v[22:25], v[168:171], v[234:237], v[22:25]
	v_mfma_f32_16x16x32_bf16 v[18:21], v[180:183], v[234:237], v[18:21]
	v_mfma_f32_16x16x32_bf16 v[18:21], v[184:187], v[238:241], v[18:21]
	v_mfma_f32_16x16x32_bf16 v[58:61], v[184:187], v[230:233], v[58:61]
	v_mfma_f32_16x16x32_bf16 v[58:61], v[180:183], v[226:229], v[58:61]
	v_mfma_f32_16x16x32_bf16 v[98:101], v[180:183], v[218:221], v[98:101]
	v_mfma_f32_16x16x32_bf16 v[98:101], v[184:187], v[222:225], v[98:101]
	v_mfma_f32_16x16x32_bf16 v[122:125], v[184:187], v[214:217], v[122:125]
	v_mfma_f32_16x16x32_bf16 v[122:125], v[180:183], v[210:213], v[122:125]
	v_mfma_f32_16x16x32_bf16 v[118:121], v[188:191], v[210:213], v[118:121]
	v_mfma_f32_16x16x32_bf16 v[118:121], v[198:201], v[214:217], v[118:121]
	v_mfma_f32_16x16x32_bf16 v[78:81], v[198:201], v[222:225], v[78:81]
	v_mfma_f32_16x16x32_bf16 v[78:81], v[188:191], v[218:221], v[78:81]
	v_mfma_f32_16x16x32_bf16 v[46:49], v[188:191], v[226:229], v[46:49]
	v_mfma_f32_16x16x32_bf16 v[46:49], v[198:201], v[230:233], v[46:49]
	v_mfma_f32_16x16x32_bf16 v[6:9], v[198:201], v[238:241], v[6:9]
	v_mfma_f32_16x16x32_bf16 v[6:9], v[188:191], v[234:237], v[6:9]
	v_mfma_f32_16x16x32_bf16 v[2:5], v[202:205], v[234:237], v[2:5]
	v_mfma_f32_16x16x32_bf16 v[2:5], v[206:209], v[238:241], v[2:5]
	v_mfma_f32_16x16x32_bf16 v[42:45], v[206:209], v[230:233], v[42:45]
	v_mfma_f32_16x16x32_bf16 v[42:45], v[202:205], v[226:229], v[42:45]
	v_mfma_f32_16x16x32_bf16 v[74:77], v[202:205], v[218:221], v[74:77]
	v_mfma_f32_16x16x32_bf16 v[74:77], v[206:209], v[222:225], v[74:77]
	v_mfma_f32_16x16x32_bf16 v[114:117], v[206:209], v[214:217], v[114:117]
	v_mfma_f32_16x16x32_bf16 v[114:117], v[202:205], v[210:213], v[114:117]
	s_barrier
	s_add_i32 s27, s27, 2
	s_add_u32 s44, s44, 0x10000
	s_addc_u32 s45, s45, 0
	s_cmp_lt_u32 s27, 30
	s_cbranch_scc1 .LBB0_682
	s_ashr_i32 s41, s40, 31
	s_lshl_b64 s[44:45], s[40:41], 21
	s_add_u32 s44, s18, s44
	s_addc_u32 s45, s19, s45
	s_ashr_i32 s39, s38, 31
	s_lshl_b64 s[46:47], s[38:39], 21
	v_readlane_b32 s58, v255, 15
	v_readlane_b32 s59, v255, 16
	s_add_u32 s46, s58, s46
	s_addc_u32 s47, s59, s47
	s_lshl_b32 s39, s26, 8
	v_or_b32_e32 v130, s39, v162
	v_ashrrev_i32_e32 v131, 31, v130
	v_lshl_add_u32 v166, s70, 8, v160
	v_lshl_add_u64 v[156:157], v[130:131], 1, s[24:25]
	v_mov_b32_e32 v168, v166
	s_and_b64 s[26:27], s[0:1], exec
	v_mad_i64_i32 v[158:159], s[58:59], v168, s78, v[156:157]
	v_add_co_u32_e32 v174, vcc, s61, v158
	s_cselect_b32 s41, s45, s51
	s_nop 0
	v_addc_co_u32_e32 v175, vcc, 0, v159, vcc
	v_add_co_u32_e32 v158, vcc, s77, v158
	v_mov_b32_e32 v230, v174
	v_mov_b32_e32 v231, v175
	global_load_dwordx4 v[130:133], v[174:175], off
	s_nop 0
	v_addc_co_u32_e32 v159, vcc, 0, v159, vcc
	global_load_dwordx4 v[170:173], v[158:159], off
	s_mov_b32 s100, 0x2000
	s_mov_b32 s101, 0
	v_lshl_add_u64 v[232:233], v[230:231], 0, s[100:101]
	s_mov_b32 s98, 0xa0000
	s_mov_b32 s99, 0
	s_mov_b32 s100, 0x320000
	s_mov_b32 s101, 0
	global_load_dwordx4 v[184:187], v[230:231], off offset:256
	global_load_dwordx4 v[188:191], v[232:233], off offset:256
	v_lshl_add_u64 v[230:231], v[230:231], 0, s[98:99]
	v_lshl_add_u64 v[232:233], v[232:233], 0, s[98:99]
	global_load_dwordx4 v[198:201], v[230:231], off
	global_load_dwordx4 v[202:205], v[232:233], off
	global_load_dwordx4 v[206:209], v[230:231], off offset:256
	global_load_dwordx4 v[210:213], v[232:233], off offset:256
	v_lshl_add_u64 v[230:231], v[230:231], 0, s[98:99]
	v_lshl_add_u64 v[232:233], v[232:233], 0, s[98:99]
	global_load_dwordx4 v[214:217], v[230:231], off
	global_load_dwordx4 v[218:221], v[232:233], off
	global_load_dwordx4 v[222:225], v[230:231], off offset:256
	global_load_dwordx4 v[226:229], v[232:233], off offset:256
	s_cselect_b32 s93, s44, s50
	s_cselect_b32 s27, s47, s49
	s_cselect_b32 s97, s46, s48
	s_add_u32 s50, s50, 0x10c000
	s_addc_u32 s51, s51, 0
	s_add_u32 s26, s48, 0x110000
	s_addc_u32 s33, s49, 0
	s_mov_b32 s56, 30
	s_waitcnt vmcnt(0)
; __device__ __forceinline__ float bflo(unsigned w) { return __uint_as_float(w << 16); }
; __device__ __forceinline__ float bfhi(unsigned w) { return __uint_as_float(w & 0xffff0000u); }
;     __device__ __forceinline__ void mid(f32x4 (&acc)[2][2][4][2], const Unit& u, int wr, int wc, int fr, int fq) const {
;     ...
;             for (int m = 0; m < 4; ++m) { const bf16_t* pr = P + (size_t)(row0 + ai * HALF + m * 16) * NP + col0;
; #pragma unroll
;                 for (int bj = 0; bj < 2; ++bj) { const u32x4 a = *(const u32x4*)(pr + PC_GA + bj * HALF), b = *(const u32x4*)(pr + PC_GB + bj * HALF);
;                     const f32x4 b0 = {bflo(b.x), bfhi(b.x), bflo(b.y), bfhi(b.y)}, b1 = {bflo(b.z), bfhi(b.z), bflo(b.w), bfhi(b.w)};
;                     const f32x4 a0 = {bflo(a.x), bfhi(a.x), bflo(a.y), bfhi(a.y)}, a1 = {bflo(a.z), bfhi(a.z), bflo(a.w), bfhi(a.w)};
;                     f32x4 r0, r1;
; #pragma unroll
;                     for (int j = 0; j < 4; ++j) { r0[j] = a0[j] * __builtin_amdgcn_rcpf(fmaxf(b0[j], 1e-30f)); r1[j] = a1[j] * __builtin_amdgcn_rcpf(fmaxf(b1[j], 1e-30f)); }
;                     acc[ai][bj][m][0] *= r0; acc[ai][bj][m][1] *= r1; }
;                 asm volatile("" ::: "memory"); }
	v_and_b32_e32 v177, 0xffff0000, v130
	v_lshlrev_b32_e32 v169, 16, v170
	v_max_f32_e32 v169, v169, v169
	v_lshlrev_b32_e32 v178, 16, v171
	v_and_b32_e32 v179, 0xffff0000, v171
	v_lshlrev_b32_e32 v171, 16, v172
	v_max_f32_e32 v169, 0xda24260, v169
	v_and_b32_e32 v176, 0xffff0000, v170
	v_rcp_f32_e32 v170, v169
	v_max_f32_e32 v169, v171, v171
	v_max_f32_e32 v169, 0xda24260, v169
	v_and_b32_e32 v180, 0xffff0000, v172
	v_rcp_f32_e32 v172, v169
	v_max_f32_e32 v169, v176, v176
	v_max_f32_e32 v169, 0xda24260, v169
	v_lshlrev_b32_e32 v176, 16, v130
	v_max_f32_e32 v130, v180, v180
	v_rcp_f32_e32 v171, v169
	v_max_f32_e32 v130, 0xda24260, v130
	v_lshlrev_b32_e32 v181, 16, v173
	v_and_b32_e32 v182, 0xffff0000, v173
	v_rcp_f32_e32 v173, v130
	v_max_f32_e32 v130, v178, v178
	v_pk_mul_f32 v[170:171], v[170:171], v[176:177]
	v_lshlrev_b32_e32 v176, 16, v132
	v_and_b32_e32 v177, 0xffff0000, v132
	v_max_f32_e32 v130, 0xda24260, v130
	v_pk_mul_f32 v[172:173], v[172:173], v[176:177]
	v_rcp_f32_e32 v176, v130
	v_max_f32_e32 v130, v181, v181
	v_lshlrev_b32_e32 v180, 16, v131
	v_and_b32_e32 v181, 0xffff0000, v131
	v_max_f32_e32 v131, v182, v182
	v_max_f32_e32 v130, 0xda24260, v130
	v_max_f32_e32 v131, 0xda24260, v131
	v_rcp_f32_e32 v130, v130
	v_rcp_f32_e32 v131, v131
	v_max_f32_e32 v132, v179, v179
	v_max_f32_e32 v132, 0xda24260, v132
	v_rcp_f32_e32 v177, v132
	v_lshlrev_b32_e32 v132, 16, v133
	v_and_b32_e32 v133, 0xffff0000, v133
	v_pk_mul_f32 v[130:131], v[130:131], v[132:133]
	v_pk_mul_f32 v[14:15], v[14:15], v[170:171]
	v_pk_mul_f32 v[12:13], v[12:13], v[130:131]
	v_pk_mul_f32 v[10:11], v[10:11], v[172:173]
	s_nop 0
	s_nop 0
	v_pk_mul_f32 v[176:177], v[176:177], v[180:181]
	s_waitcnt vmcnt(9)
	v_mov_b32_e32 v130, v184
	v_mov_b32_e32 v131, v185
	v_mov_b32_e32 v132, v186
	v_mov_b32_e32 v133, v187
	v_lshl_add_u64 v[230:231], v[230:231], 0, s[98:99]
	v_lshl_add_u64 v[232:233], v[232:233], 0, s[98:99]
	global_load_dwordx4 v[184:187], v[230:231], off
	s_waitcnt vmcnt(9)
	v_mov_b32_e32 v170, v188
	v_mov_b32_e32 v171, v189
	v_mov_b32_e32 v172, v190
	v_mov_b32_e32 v173, v191
	global_load_dwordx4 v[188:191], v[232:233], off
	v_lshlrev_b32_e32 v158, 16, v170
	v_and_b32_e32 v159, 0xffff0000, v170
	v_lshlrev_b32_e32 v169, 16, v171
	v_and_b32_e32 v174, 0xffff0000, v171
	v_lshlrev_b32_e32 v170, 16, v172
	v_and_b32_e32 v171, 0xffff0000, v172
	v_max_f32_e32 v158, v158, v158
	v_max_f32_e32 v159, v159, v159
	v_pk_mul_f32 v[16:17], v[16:17], v[176:177]
	v_lshlrev_b32_e32 v175, 16, v173
	v_and_b32_e32 v176, 0xffff0000, v173
	v_max_f32_e32 v158, 0xda24260, v158
	v_max_f32_e32 v170, v170, v170
	v_max_f32_e32 v159, 0xda24260, v159
	v_lshlrev_b32_e32 v172, 16, v130
	v_and_b32_e32 v173, 0xffff0000, v130
	v_max_f32_e32 v130, v171, v171
	v_rcp_f32_e32 v158, v158
	v_max_f32_e32 v170, 0xda24260, v170
	v_rcp_f32_e32 v159, v159
	v_max_f32_e32 v130, 0xda24260, v130
	v_rcp_f32_e32 v170, v170
	v_rcp_f32_e32 v171, v130
	v_max_f32_e32 v130, v169, v169
	v_pk_mul_f32 v[158:159], v[158:159], v[172:173]
	v_lshlrev_b32_e32 v172, 16, v132
	v_and_b32_e32 v173, 0xffff0000, v132
	v_max_f32_e32 v130, 0xda24260, v130
	v_pk_mul_f32 v[170:171], v[170:171], v[172:173]
	v_rcp_f32_e32 v172, v130
	v_max_f32_e32 v130, v175, v175
	v_max_f32_e32 v132, v174, v174
	v_lshlrev_b32_e32 v174, 16, v131
	v_and_b32_e32 v175, 0xffff0000, v131
	v_max_f32_e32 v131, v176, v176
	v_max_f32_e32 v130, 0xda24260, v130
	v_max_f32_e32 v131, 0xda24260, v131
	v_rcp_f32_e32 v130, v130
	v_rcp_f32_e32 v131, v131
	v_max_f32_e32 v132, 0xda24260, v132
	v_rcp_f32_e32 v173, v132
	v_lshlrev_b32_e32 v132, 16, v133
	v_and_b32_e32 v133, 0xffff0000, v133
	v_pk_mul_f32 v[130:131], v[130:131], v[132:133]
	v_pk_mul_f32 v[30:31], v[30:31], v[158:159]
	v_pk_mul_f32 v[28:29], v[28:29], v[130:131]
	v_add_u32_e32 v130, 16, v168
	v_mad_i64_i32 v[158:159], s[58:59], v130, s78, v[156:157]
	v_pk_mul_f32 v[172:173], v[172:173], v[174:175]
	v_add_co_u32_e32 v174, vcc, s61, v158
	v_pk_mul_f32 v[32:33], v[32:33], v[172:173]
	s_nop 0
	v_addc_co_u32_e32 v175, vcc, 0, v159, vcc
	v_add_co_u32_e32 v158, vcc, s77, v158
	v_pk_mul_f32 v[26:27], v[26:27], v[170:171]
	s_nop 0
	v_addc_co_u32_e32 v159, vcc, 0, v159, vcc
	s_nop 0
	s_nop 0
	s_waitcnt vmcnt(9)
	v_mov_b32_e32 v130, v198
	v_mov_b32_e32 v131, v199
	v_mov_b32_e32 v132, v200
	v_mov_b32_e32 v133, v201
	global_load_dwordx4 v[198:201], v[230:231], off offset:256
	v_and_b32_e32 v177, 0xffff0000, v130
	s_waitcnt vmcnt(9)
	v_mov_b32_e32 v170, v202
	v_mov_b32_e32 v171, v203
	v_mov_b32_e32 v172, v204
	v_mov_b32_e32 v173, v205
	global_load_dwordx4 v[202:205], v[232:233], off offset:256
	v_lshlrev_b32_e32 v169, 16, v170
	v_max_f32_e32 v169, v169, v169
	v_lshlrev_b32_e32 v178, 16, v171
	v_and_b32_e32 v179, 0xffff0000, v171
	v_lshlrev_b32_e32 v171, 16, v172
	v_max_f32_e32 v169, 0xda24260, v169
	v_and_b32_e32 v176, 0xffff0000, v170
	v_rcp_f32_e32 v170, v169
	v_max_f32_e32 v169, v171, v171
	v_max_f32_e32 v169, 0xda24260, v169
	v_and_b32_e32 v180, 0xffff0000, v172
	v_rcp_f32_e32 v172, v169
	v_max_f32_e32 v169, v176, v176
	v_max_f32_e32 v169, 0xda24260, v169
	v_lshlrev_b32_e32 v176, 16, v130
	v_max_f32_e32 v130, v180, v180
	v_rcp_f32_e32 v171, v169
	v_max_f32_e32 v130, 0xda24260, v130
	v_lshlrev_b32_e32 v181, 16, v173
	v_and_b32_e32 v182, 0xffff0000, v173
	v_rcp_f32_e32 v173, v130
	v_max_f32_e32 v130, v178, v178
	v_pk_mul_f32 v[170:171], v[170:171], v[176:177]
	v_lshlrev_b32_e32 v176, 16, v132
	v_and_b32_e32 v177, 0xffff0000, v132
	v_max_f32_e32 v130, 0xda24260, v130
	v_pk_mul_f32 v[172:173], v[172:173], v[176:177]
	v_rcp_f32_e32 v176, v130
	v_max_f32_e32 v130, v181, v181
	v_lshlrev_b32_e32 v180, 16, v131
	v_and_b32_e32 v181, 0xffff0000, v131
	v_max_f32_e32 v131, v182, v182
	v_max_f32_e32 v130, 0xda24260, v130
	v_max_f32_e32 v131, 0xda24260, v131
	v_rcp_f32_e32 v130, v130
	v_rcp_f32_e32 v131, v131
	v_max_f32_e32 v132, v179, v179
	v_max_f32_e32 v132, 0xda24260, v132
	v_rcp_f32_e32 v177, v132
	v_lshlrev_b32_e32 v132, 16, v133
	v_and_b32_e32 v133, 0xffff0000, v133
	v_pk_mul_f32 v[130:131], v[130:131], v[132:133]
	v_pk_mul_f32 v[38:39], v[38:39], v[170:171]
	v_pk_mul_f32 v[36:37], v[36:37], v[130:131]
	v_pk_mul_f32 v[34:35], v[34:35], v[172:173]
	s_nop 0
	s_nop 0
	v_pk_mul_f32 v[176:177], v[176:177], v[180:181]
	s_waitcnt vmcnt(9)
; __device__ __forceinline__ float bflo(unsigned w) { return __uint_as_float(w << 16); }
; __device__ __forceinline__ float bfhi(unsigned w) { return __uint_as_float(w & 0xffff0000u); }
;     __device__ __forceinline__ void mid(f32x4 (&acc)[2][2][4][2], const Unit& u, int wr, int wc, int fr, int fq) const {
;     ...
;             for (int m = 0; m < 4; ++m) { const bf16_t* pr = P + (size_t)(row0 + ai * HALF + m * 16) * NP + col0;
; #pragma unroll
;                 for (int bj = 0; bj < 2; ++bj) { const u32x4 a = *(const u32x4*)(pr + PC_GA + bj * HALF), b = *(const u32x4*)(pr + PC_GB + bj * HALF);
;                     const f32x4 b0 = {bflo(b.x), bfhi(b.x), bflo(b.y), bfhi(b.y)}, b1 = {bflo(b.z), bfhi(b.z), bflo(b.w), bfhi(b.w)};
;                     const f32x4 a0 = {bflo(a.x), bfhi(a.x), bflo(a.y), bfhi(a.y)}, a1 = {bflo(a.z), bfhi(a.z), bflo(a.w), bfhi(a.w)};
;                     f32x4 r0, r1;
; #pragma unroll
;                     for (int j = 0; j < 4; ++j) { r0[j] = a0[j] * __builtin_amdgcn_rcpf(fmaxf(b0[j], 1e-30f)); r1[j] = a1[j] * __builtin_amdgcn_rcpf(fmaxf(b1[j], 1e-30f)); }
;                     acc[ai][bj][m][0] *= r0; acc[ai][bj][m][1] *= r1; }
;                 asm volatile("" ::: "memory"); }
	v_mov_b32_e32 v130, v206
	v_mov_b32_e32 v131, v207
	v_mov_b32_e32 v132, v208
	v_mov_b32_e32 v133, v209
	v_lshl_add_u64 v[230:231], v[230:231], 0, s[100:101]
	v_lshl_add_u64 v[232:233], v[232:233], 0, s[100:101]
	global_load_dwordx4 v[206:209], v[230:231], off
	s_waitcnt vmcnt(9)
	v_mov_b32_e32 v170, v210
	v_mov_b32_e32 v171, v211
	v_mov_b32_e32 v172, v212
	v_mov_b32_e32 v173, v213
	global_load_dwordx4 v[210:213], v[232:233], off
	v_lshlrev_b32_e32 v158, 16, v170
	v_and_b32_e32 v159, 0xffff0000, v170
	v_lshlrev_b32_e32 v169, 16, v171
	v_and_b32_e32 v174, 0xffff0000, v171
	v_lshlrev_b32_e32 v170, 16, v172
	v_and_b32_e32 v171, 0xffff0000, v172
	v_max_f32_e32 v158, v158, v158
	v_max_f32_e32 v159, v159, v159
	v_pk_mul_f32 v[40:41], v[40:41], v[176:177]
	v_lshlrev_b32_e32 v175, 16, v173
	v_and_b32_e32 v176, 0xffff0000, v173
	v_max_f32_e32 v158, 0xda24260, v158
	v_max_f32_e32 v170, v170, v170
	v_max_f32_e32 v159, 0xda24260, v159
	v_lshlrev_b32_e32 v172, 16, v130
	v_and_b32_e32 v173, 0xffff0000, v130
	v_max_f32_e32 v130, v171, v171
	v_rcp_f32_e32 v158, v158
	v_max_f32_e32 v170, 0xda24260, v170
	v_rcp_f32_e32 v159, v159
	v_max_f32_e32 v130, 0xda24260, v130
	v_rcp_f32_e32 v170, v170
	v_rcp_f32_e32 v171, v130
	v_max_f32_e32 v130, v169, v169
	v_pk_mul_f32 v[158:159], v[158:159], v[172:173]
	v_lshlrev_b32_e32 v172, 16, v132
	v_and_b32_e32 v173, 0xffff0000, v132
	v_max_f32_e32 v130, 0xda24260, v130
	v_pk_mul_f32 v[170:171], v[170:171], v[172:173]
	v_rcp_f32_e32 v172, v130
	v_max_f32_e32 v130, v175, v175
	v_max_f32_e32 v132, v174, v174
	v_lshlrev_b32_e32 v174, 16, v131
	v_and_b32_e32 v175, 0xffff0000, v131
	v_max_f32_e32 v131, v176, v176
	v_max_f32_e32 v130, 0xda24260, v130
	v_max_f32_e32 v131, 0xda24260, v131
	v_rcp_f32_e32 v130, v130
	v_rcp_f32_e32 v131, v131
	v_max_f32_e32 v132, 0xda24260, v132
	v_rcp_f32_e32 v173, v132
	v_lshlrev_b32_e32 v132, 16, v133
	v_and_b32_e32 v133, 0xffff0000, v133
	v_pk_mul_f32 v[130:131], v[130:131], v[132:133]
	v_pk_mul_f32 v[54:55], v[54:55], v[158:159]
	v_pk_mul_f32 v[52:53], v[52:53], v[130:131]
	v_add_u32_e32 v130, 32, v168
	v_mad_i64_i32 v[158:159], s[58:59], v130, s78, v[156:157]
	v_pk_mul_f32 v[172:173], v[172:173], v[174:175]
	v_add_co_u32_e32 v174, vcc, s61, v158
	v_pk_mul_f32 v[56:57], v[56:57], v[172:173]
	s_nop 0
	v_addc_co_u32_e32 v175, vcc, 0, v159, vcc
	v_add_co_u32_e32 v158, vcc, s77, v158
	v_pk_mul_f32 v[50:51], v[50:51], v[170:171]
	s_nop 0
	v_addc_co_u32_e32 v159, vcc, 0, v159, vcc
	s_nop 0
	s_nop 0
	s_waitcnt vmcnt(9)
	v_mov_b32_e32 v130, v214
	v_mov_b32_e32 v131, v215
	v_mov_b32_e32 v132, v216
	v_mov_b32_e32 v133, v217
	global_load_dwordx4 v[214:217], v[230:231], off offset:256
	v_and_b32_e32 v177, 0xffff0000, v130
	s_waitcnt vmcnt(9)
	v_mov_b32_e32 v170, v218
	v_mov_b32_e32 v171, v219
	v_mov_b32_e32 v172, v220
	v_mov_b32_e32 v173, v221
	global_load_dwordx4 v[218:221], v[232:233], off offset:256
	v_lshlrev_b32_e32 v169, 16, v170
	v_max_f32_e32 v169, v169, v169
	v_lshlrev_b32_e32 v178, 16, v171
	v_and_b32_e32 v179, 0xffff0000, v171
	v_lshlrev_b32_e32 v171, 16, v172
	v_max_f32_e32 v169, 0xda24260, v169
	v_and_b32_e32 v176, 0xffff0000, v170
	v_rcp_f32_e32 v170, v169
	v_max_f32_e32 v169, v171, v171
	v_max_f32_e32 v169, 0xda24260, v169
	v_and_b32_e32 v180, 0xffff0000, v172
	v_rcp_f32_e32 v172, v169
	v_max_f32_e32 v169, v176, v176
	v_max_f32_e32 v169, 0xda24260, v169
	v_lshlrev_b32_e32 v176, 16, v130
	v_max_f32_e32 v130, v180, v180
	v_rcp_f32_e32 v171, v169
	v_max_f32_e32 v130, 0xda24260, v130
	v_lshlrev_b32_e32 v181, 16, v173
	v_and_b32_e32 v182, 0xffff0000, v173
	v_rcp_f32_e32 v173, v130
	v_max_f32_e32 v130, v178, v178
	v_pk_mul_f32 v[170:171], v[170:171], v[176:177]
	v_lshlrev_b32_e32 v176, 16, v132
	v_and_b32_e32 v177, 0xffff0000, v132
	v_max_f32_e32 v130, 0xda24260, v130
	v_pk_mul_f32 v[172:173], v[172:173], v[176:177]
	v_rcp_f32_e32 v176, v130
	v_max_f32_e32 v130, v181, v181
	v_lshlrev_b32_e32 v180, 16, v131
	v_and_b32_e32 v181, 0xffff0000, v131
	v_max_f32_e32 v131, v182, v182
	v_max_f32_e32 v130, 0xda24260, v130
	v_max_f32_e32 v131, 0xda24260, v131
	v_rcp_f32_e32 v130, v130
	v_rcp_f32_e32 v131, v131
	v_max_f32_e32 v132, v179, v179
	v_max_f32_e32 v132, 0xda24260, v132
	v_rcp_f32_e32 v177, v132
	v_lshlrev_b32_e32 v132, 16, v133
	v_and_b32_e32 v133, 0xffff0000, v133
	v_pk_mul_f32 v[130:131], v[130:131], v[132:133]
	v_pk_mul_f32 v[70:71], v[70:71], v[170:171]
	v_pk_mul_f32 v[68:69], v[68:69], v[130:131]
	v_pk_mul_f32 v[66:67], v[66:67], v[172:173]
	s_nop 0
	s_nop 0
	v_pk_mul_f32 v[176:177], v[176:177], v[180:181]
	s_waitcnt vmcnt(9)
	v_mov_b32_e32 v130, v222
	v_mov_b32_e32 v131, v223
	v_mov_b32_e32 v132, v224
	v_mov_b32_e32 v133, v225
	v_lshl_add_u64 v[230:231], v[230:231], 0, s[98:99]
	v_lshl_add_u64 v[232:233], v[232:233], 0, s[98:99]
	global_load_dwordx4 v[222:225], v[230:231], off
	s_waitcnt vmcnt(9)
; __device__ __forceinline__ float bflo(unsigned w) { return __uint_as_float(w << 16); }
; __device__ __forceinline__ float bfhi(unsigned w) { return __uint_as_float(w & 0xffff0000u); }
;     __device__ __forceinline__ void mid(f32x4 (&acc)[2][2][4][2], const Unit& u, int wr, int wc, int fr, int fq) const {
;     ...
;             for (int m = 0; m < 4; ++m) { const bf16_t* pr = P + (size_t)(row0 + ai * HALF + m * 16) * NP + col0;
; #pragma unroll
;                 for (int bj = 0; bj < 2; ++bj) { const u32x4 a = *(const u32x4*)(pr + PC_GA + bj * HALF), b = *(const u32x4*)(pr + PC_GB + bj * HALF);
;                     const f32x4 b0 = {bflo(b.x), bfhi(b.x), bflo(b.y), bfhi(b.y)}, b1 = {bflo(b.z), bfhi(b.z), bflo(b.w), bfhi(b.w)};
;                     const f32x4 a0 = {bflo(a.x), bfhi(a.x), bflo(a.y), bfhi(a.y)}, a1 = {bflo(a.z), bfhi(a.z), bflo(a.w), bfhi(a.w)};
;                     f32x4 r0, r1;
; #pragma unroll
;                     for (int j = 0; j < 4; ++j) { r0[j] = a0[j] * __builtin_amdgcn_rcpf(fmaxf(b0[j], 1e-30f)); r1[j] = a1[j] * __builtin_amdgcn_rcpf(fmaxf(b1[j], 1e-30f)); }
;                     acc[ai][bj][m][0] *= r0; acc[ai][bj][m][1] *= r1; }
;                 asm volatile("" ::: "memory"); }
	v_mov_b32_e32 v170, v226
	v_mov_b32_e32 v171, v227
	v_mov_b32_e32 v172, v228
	v_mov_b32_e32 v173, v229
	global_load_dwordx4 v[226:229], v[232:233], off
	v_lshlrev_b32_e32 v158, 16, v170
	v_and_b32_e32 v159, 0xffff0000, v170
	v_lshlrev_b32_e32 v169, 16, v171
	v_and_b32_e32 v174, 0xffff0000, v171
	v_lshlrev_b32_e32 v170, 16, v172
	v_and_b32_e32 v171, 0xffff0000, v172
	v_max_f32_e32 v158, v158, v158
	v_max_f32_e32 v159, v159, v159
	v_pk_mul_f32 v[72:73], v[72:73], v[176:177]
	v_lshlrev_b32_e32 v175, 16, v173
	v_and_b32_e32 v176, 0xffff0000, v173
	v_max_f32_e32 v158, 0xda24260, v158
	v_max_f32_e32 v170, v170, v170
	v_max_f32_e32 v159, 0xda24260, v159
	v_lshlrev_b32_e32 v172, 16, v130
	v_and_b32_e32 v173, 0xffff0000, v130
	v_max_f32_e32 v130, v171, v171
	v_rcp_f32_e32 v158, v158
	v_max_f32_e32 v170, 0xda24260, v170
	v_rcp_f32_e32 v159, v159
	v_max_f32_e32 v130, 0xda24260, v130
	v_rcp_f32_e32 v170, v170
	v_rcp_f32_e32 v171, v130
	v_max_f32_e32 v130, v169, v169
	v_pk_mul_f32 v[158:159], v[158:159], v[172:173]
	v_lshlrev_b32_e32 v172, 16, v132
	v_and_b32_e32 v173, 0xffff0000, v132
	v_max_f32_e32 v130, 0xda24260, v130
	v_pk_mul_f32 v[170:171], v[170:171], v[172:173]
	v_rcp_f32_e32 v172, v130
	v_max_f32_e32 v130, v175, v175
	v_max_f32_e32 v132, v174, v174
	v_lshlrev_b32_e32 v174, 16, v131
	v_and_b32_e32 v175, 0xffff0000, v131
	v_max_f32_e32 v131, v176, v176
	v_max_f32_e32 v130, 0xda24260, v130
	v_max_f32_e32 v131, 0xda24260, v131
	v_rcp_f32_e32 v130, v130
	v_rcp_f32_e32 v131, v131
	v_max_f32_e32 v132, 0xda24260, v132
	v_rcp_f32_e32 v173, v132
	v_lshlrev_b32_e32 v132, 16, v133
	v_and_b32_e32 v133, 0xffff0000, v133
	v_pk_mul_f32 v[130:131], v[130:131], v[132:133]
	v_pk_mul_f32 v[86:87], v[86:87], v[158:159]
	v_pk_mul_f32 v[84:85], v[84:85], v[130:131]
	v_add_u32_e32 v130, 48, v168
	v_mad_i64_i32 v[158:159], s[58:59], v130, s78, v[156:157]
	v_pk_mul_f32 v[172:173], v[172:173], v[174:175]
	v_add_co_u32_e32 v174, vcc, s61, v158
	v_pk_mul_f32 v[88:89], v[88:89], v[172:173]
	s_nop 0
	v_addc_co_u32_e32 v175, vcc, 0, v159, vcc
	v_add_co_u32_e32 v158, vcc, s77, v158
	v_pk_mul_f32 v[82:83], v[82:83], v[170:171]
	s_nop 0
	v_addc_co_u32_e32 v159, vcc, 0, v159, vcc
	s_nop 0
	s_nop 0
	s_waitcnt vmcnt(9)
	v_mov_b32_e32 v130, v184
	v_mov_b32_e32 v131, v185
	v_mov_b32_e32 v132, v186
	v_mov_b32_e32 v133, v187
	global_load_dwordx4 v[184:187], v[230:231], off offset:256
	v_and_b32_e32 v177, 0xffff0000, v130
	s_waitcnt vmcnt(9)
	v_mov_b32_e32 v170, v188
	v_mov_b32_e32 v171, v189
	v_mov_b32_e32 v172, v190
	v_mov_b32_e32 v173, v191
	global_load_dwordx4 v[188:191], v[232:233], off offset:256
	v_lshlrev_b32_e32 v169, 16, v170
	v_max_f32_e32 v169, v169, v169
	v_lshlrev_b32_e32 v178, 16, v171
	v_and_b32_e32 v179, 0xffff0000, v171
	v_lshlrev_b32_e32 v171, 16, v172
	v_max_f32_e32 v169, 0xda24260, v169
	v_and_b32_e32 v176, 0xffff0000, v170
	v_rcp_f32_e32 v170, v169
	v_max_f32_e32 v169, v171, v171
	v_max_f32_e32 v169, 0xda24260, v169
	v_and_b32_e32 v180, 0xffff0000, v172
	v_rcp_f32_e32 v172, v169
	v_max_f32_e32 v169, v176, v176
	v_max_f32_e32 v169, 0xda24260, v169
	v_lshlrev_b32_e32 v176, 16, v130
	v_max_f32_e32 v130, v180, v180
	v_rcp_f32_e32 v171, v169
	v_max_f32_e32 v130, 0xda24260, v130
	v_lshlrev_b32_e32 v181, 16, v173
	v_and_b32_e32 v182, 0xffff0000, v173
	v_rcp_f32_e32 v173, v130
	v_max_f32_e32 v130, v178, v178
	v_pk_mul_f32 v[170:171], v[170:171], v[176:177]
	v_lshlrev_b32_e32 v176, 16, v132
	v_and_b32_e32 v177, 0xffff0000, v132
	v_max_f32_e32 v130, 0xda24260, v130
	v_pk_mul_f32 v[172:173], v[172:173], v[176:177]
	v_rcp_f32_e32 v176, v130
	v_max_f32_e32 v130, v181, v181
	v_lshlrev_b32_e32 v180, 16, v131
	v_and_b32_e32 v181, 0xffff0000, v131
	v_max_f32_e32 v131, v182, v182
	v_max_f32_e32 v130, 0xda24260, v130
	v_max_f32_e32 v131, 0xda24260, v131
	v_rcp_f32_e32 v130, v130
	v_rcp_f32_e32 v131, v131
	v_max_f32_e32 v132, v179, v179
	v_max_f32_e32 v132, 0xda24260, v132
	v_rcp_f32_e32 v177, v132
	v_lshlrev_b32_e32 v132, 16, v133
	v_and_b32_e32 v133, 0xffff0000, v133
	v_pk_mul_f32 v[130:131], v[130:131], v[132:133]
	v_pk_mul_f32 v[94:95], v[94:95], v[170:171]
	v_pk_mul_f32 v[92:93], v[92:93], v[130:131]
	v_pk_mul_f32 v[90:91], v[90:91], v[172:173]
	s_nop 0
	s_nop 0
	v_pk_mul_f32 v[176:177], v[176:177], v[180:181]
	s_waitcnt vmcnt(9)
	v_mov_b32_e32 v130, v198
	v_mov_b32_e32 v131, v199
	v_mov_b32_e32 v132, v200
	v_mov_b32_e32 v133, v201
	v_lshl_add_u64 v[230:231], v[230:231], 0, s[98:99]
	v_lshl_add_u64 v[232:233], v[232:233], 0, s[98:99]
	global_load_dwordx4 v[198:201], v[230:231], off
	s_waitcnt vmcnt(9)
; __device__ __forceinline__ float bflo(unsigned w) { return __uint_as_float(w << 16); }
; __device__ __forceinline__ float bfhi(unsigned w) { return __uint_as_float(w & 0xffff0000u); }
;     __device__ __forceinline__ void mid(f32x4 (&acc)[2][2][4][2], const Unit& u, int wr, int wc, int fr, int fq) const {
;     ...
;             for (int m = 0; m < 4; ++m) { const bf16_t* pr = P + (size_t)(row0 + ai * HALF + m * 16) * NP + col0;
; #pragma unroll
;                 for (int bj = 0; bj < 2; ++bj) { const u32x4 a = *(const u32x4*)(pr + PC_GA + bj * HALF), b = *(const u32x4*)(pr + PC_GB + bj * HALF);
;                     const f32x4 b0 = {bflo(b.x), bfhi(b.x), bflo(b.y), bfhi(b.y)}, b1 = {bflo(b.z), bfhi(b.z), bflo(b.w), bfhi(b.w)};
;                     const f32x4 a0 = {bflo(a.x), bfhi(a.x), bflo(a.y), bfhi(a.y)}, a1 = {bflo(a.z), bfhi(a.z), bflo(a.w), bfhi(a.w)};
;                     f32x4 r0, r1;
; #pragma unroll
;                     for (int j = 0; j < 4; ++j) { r0[j] = a0[j] * __builtin_amdgcn_rcpf(fmaxf(b0[j], 1e-30f)); r1[j] = a1[j] * __builtin_amdgcn_rcpf(fmaxf(b1[j], 1e-30f)); }
;                     acc[ai][bj][m][0] *= r0; acc[ai][bj][m][1] *= r1; }
;                 asm volatile("" ::: "memory"); }
	v_mov_b32_e32 v170, v202
	v_mov_b32_e32 v171, v203
	v_mov_b32_e32 v172, v204
	v_mov_b32_e32 v173, v205
	global_load_dwordx4 v[202:205], v[232:233], off
	v_lshlrev_b32_e32 v158, 16, v170
	v_and_b32_e32 v159, 0xffff0000, v170
	v_lshlrev_b32_e32 v169, 16, v171
	v_and_b32_e32 v174, 0xffff0000, v171
	v_lshlrev_b32_e32 v170, 16, v172
	v_and_b32_e32 v171, 0xffff0000, v172
	v_max_f32_e32 v158, v158, v158
	v_max_f32_e32 v159, v159, v159
	v_pk_mul_f32 v[96:97], v[96:97], v[176:177]
	v_lshlrev_b32_e32 v175, 16, v173
	v_and_b32_e32 v176, 0xffff0000, v173
	v_max_f32_e32 v158, 0xda24260, v158
	v_max_f32_e32 v170, v170, v170
	v_max_f32_e32 v159, 0xda24260, v159
	v_lshlrev_b32_e32 v172, 16, v130
	v_and_b32_e32 v173, 0xffff0000, v130
	v_max_f32_e32 v130, v171, v171
	v_rcp_f32_e32 v158, v158
	v_max_f32_e32 v170, 0xda24260, v170
	v_rcp_f32_e32 v159, v159
	v_max_f32_e32 v130, 0xda24260, v130
	v_rcp_f32_e32 v170, v170
	v_rcp_f32_e32 v171, v130
	v_max_f32_e32 v130, v169, v169
	v_pk_mul_f32 v[158:159], v[158:159], v[172:173]
	v_lshlrev_b32_e32 v172, 16, v132
	v_and_b32_e32 v173, 0xffff0000, v132
	v_max_f32_e32 v130, 0xda24260, v130
	v_pk_mul_f32 v[170:171], v[170:171], v[172:173]
	v_rcp_f32_e32 v172, v130
	v_max_f32_e32 v130, v175, v175
	v_max_f32_e32 v132, v174, v174
	v_lshlrev_b32_e32 v174, 16, v131
	v_and_b32_e32 v175, 0xffff0000, v131
	v_max_f32_e32 v131, v176, v176
	v_max_f32_e32 v130, 0xda24260, v130
	v_max_f32_e32 v131, 0xda24260, v131
	v_rcp_f32_e32 v130, v130
	v_rcp_f32_e32 v131, v131
	v_max_f32_e32 v132, 0xda24260, v132
	v_rcp_f32_e32 v173, v132
	v_lshlrev_b32_e32 v132, 16, v133
	v_and_b32_e32 v133, 0xffff0000, v133
	v_pk_mul_f32 v[130:131], v[130:131], v[132:133]
	v_pk_mul_f32 v[110:111], v[110:111], v[158:159]
	v_pk_mul_f32 v[108:109], v[108:109], v[130:131]
	v_add_u32_e32 v130, 0x80, v168
	v_mad_i64_i32 v[158:159], s[58:59], v130, s78, v[156:157]
	v_pk_mul_f32 v[172:173], v[172:173], v[174:175]
	v_add_co_u32_e32 v174, vcc, s61, v158
	v_pk_mul_f32 v[112:113], v[112:113], v[172:173]
	s_nop 0
	v_addc_co_u32_e32 v175, vcc, 0, v159, vcc
	v_add_co_u32_e32 v158, vcc, s77, v158
	v_pk_mul_f32 v[106:107], v[106:107], v[170:171]
	s_nop 0
	v_addc_co_u32_e32 v159, vcc, 0, v159, vcc
	s_nop 0
	s_nop 0
	s_waitcnt vmcnt(9)
	v_mov_b32_e32 v130, v206
	v_mov_b32_e32 v131, v207
	v_mov_b32_e32 v132, v208
	v_mov_b32_e32 v133, v209
	global_load_dwordx4 v[206:209], v[230:231], off offset:256
	v_and_b32_e32 v177, 0xffff0000, v130
	s_waitcnt vmcnt(9)
	v_mov_b32_e32 v170, v210
	v_mov_b32_e32 v171, v211
	v_mov_b32_e32 v172, v212
	v_mov_b32_e32 v173, v213
	global_load_dwordx4 v[210:213], v[232:233], off offset:256
	v_lshlrev_b32_e32 v169, 16, v170
	v_max_f32_e32 v169, v169, v169
	v_lshlrev_b32_e32 v178, 16, v171
	v_and_b32_e32 v179, 0xffff0000, v171
	v_lshlrev_b32_e32 v171, 16, v172
	v_max_f32_e32 v169, 0xda24260, v169
	v_and_b32_e32 v176, 0xffff0000, v170
	v_rcp_f32_e32 v170, v169
	v_max_f32_e32 v169, v171, v171
	v_max_f32_e32 v169, 0xda24260, v169
	v_and_b32_e32 v180, 0xffff0000, v172
	v_rcp_f32_e32 v172, v169
	v_max_f32_e32 v169, v176, v176
	v_max_f32_e32 v169, 0xda24260, v169
	v_lshlrev_b32_e32 v176, 16, v130
	v_max_f32_e32 v130, v180, v180
	v_rcp_f32_e32 v171, v169
	v_max_f32_e32 v130, 0xda24260, v130
	v_lshlrev_b32_e32 v181, 16, v173
	v_and_b32_e32 v182, 0xffff0000, v173
	v_rcp_f32_e32 v173, v130
	v_max_f32_e32 v130, v178, v178
	v_pk_mul_f32 v[170:171], v[170:171], v[176:177]
	v_lshlrev_b32_e32 v176, 16, v132
	v_and_b32_e32 v177, 0xffff0000, v132
	v_max_f32_e32 v130, 0xda24260, v130
	v_pk_mul_f32 v[172:173], v[172:173], v[176:177]
	v_rcp_f32_e32 v176, v130
	v_max_f32_e32 v130, v181, v181
	v_lshlrev_b32_e32 v180, 16, v131
	v_and_b32_e32 v181, 0xffff0000, v131
	v_max_f32_e32 v131, v182, v182
	v_max_f32_e32 v130, 0xda24260, v130
	v_max_f32_e32 v131, 0xda24260, v131
	v_rcp_f32_e32 v130, v130
	v_rcp_f32_e32 v131, v131
	v_max_f32_e32 v132, v179, v179
	v_max_f32_e32 v132, 0xda24260, v132
	v_rcp_f32_e32 v177, v132
	v_lshlrev_b32_e32 v132, 16, v133
	v_and_b32_e32 v133, 0xffff0000, v133
	v_pk_mul_f32 v[130:131], v[130:131], v[132:133]
	v_pk_mul_f32 v[126:127], v[126:127], v[170:171]
	v_pk_mul_f32 v[124:125], v[124:125], v[130:131]
	v_pk_mul_f32 v[122:123], v[122:123], v[172:173]
	s_nop 0
	s_nop 0
	v_pk_mul_f32 v[176:177], v[176:177], v[180:181]
	s_waitcnt vmcnt(9)
	v_mov_b32_e32 v130, v214
	v_mov_b32_e32 v131, v215
	v_mov_b32_e32 v132, v216
	v_mov_b32_e32 v133, v217
	v_lshl_add_u64 v[230:231], v[230:231], 0, s[98:99]
	v_lshl_add_u64 v[232:233], v[232:233], 0, s[98:99]
	global_load_dwordx4 v[214:217], v[230:231], off
	s_waitcnt vmcnt(9)
; __device__ __forceinline__ float bflo(unsigned w) { return __uint_as_float(w << 16); }
; __device__ __forceinline__ float bfhi(unsigned w) { return __uint_as_float(w & 0xffff0000u); }
;     __device__ __forceinline__ void mid(f32x4 (&acc)[2][2][4][2], const Unit& u, int wr, int wc, int fr, int fq) const {
;     ...
;             for (int m = 0; m < 4; ++m) { const bf16_t* pr = P + (size_t)(row0 + ai * HALF + m * 16) * NP + col0;
; #pragma unroll
;                 for (int bj = 0; bj < 2; ++bj) { const u32x4 a = *(const u32x4*)(pr + PC_GA + bj * HALF), b = *(const u32x4*)(pr + PC_GB + bj * HALF);
;                     const f32x4 b0 = {bflo(b.x), bfhi(b.x), bflo(b.y), bfhi(b.y)}, b1 = {bflo(b.z), bfhi(b.z), bflo(b.w), bfhi(b.w)};
;                     const f32x4 a0 = {bflo(a.x), bfhi(a.x), bflo(a.y), bfhi(a.y)}, a1 = {bflo(a.z), bfhi(a.z), bflo(a.w), bfhi(a.w)};
;                     f32x4 r0, r1;
; #pragma unroll
;                     for (int j = 0; j < 4; ++j) { r0[j] = a0[j] * __builtin_amdgcn_rcpf(fmaxf(b0[j], 1e-30f)); r1[j] = a1[j] * __builtin_amdgcn_rcpf(fmaxf(b1[j], 1e-30f)); }
;                     acc[ai][bj][m][0] *= r0; acc[ai][bj][m][1] *= r1; }
;                 asm volatile("" ::: "memory"); }
	v_mov_b32_e32 v170, v218
	v_mov_b32_e32 v171, v219
	v_mov_b32_e32 v172, v220
	v_mov_b32_e32 v173, v221
	global_load_dwordx4 v[218:221], v[232:233], off
	v_lshlrev_b32_e32 v158, 16, v170
	v_and_b32_e32 v159, 0xffff0000, v170
	v_lshlrev_b32_e32 v169, 16, v171
	v_and_b32_e32 v174, 0xffff0000, v171
	v_lshlrev_b32_e32 v170, 16, v172
	v_and_b32_e32 v171, 0xffff0000, v172
	v_max_f32_e32 v158, v158, v158
	v_max_f32_e32 v159, v159, v159
	v_pk_mul_f32 v[128:129], v[128:129], v[176:177]
	v_lshlrev_b32_e32 v175, 16, v173
	v_and_b32_e32 v176, 0xffff0000, v173
	v_max_f32_e32 v158, 0xda24260, v158
	v_max_f32_e32 v170, v170, v170
	v_max_f32_e32 v159, 0xda24260, v159
	v_lshlrev_b32_e32 v172, 16, v130
	v_and_b32_e32 v173, 0xffff0000, v130
	v_max_f32_e32 v130, v171, v171
	v_rcp_f32_e32 v158, v158
	v_max_f32_e32 v170, 0xda24260, v170
	v_rcp_f32_e32 v159, v159
	v_max_f32_e32 v130, 0xda24260, v130
	v_rcp_f32_e32 v170, v170
	v_rcp_f32_e32 v171, v130
	v_max_f32_e32 v130, v169, v169
	v_pk_mul_f32 v[158:159], v[158:159], v[172:173]
	v_lshlrev_b32_e32 v172, 16, v132
	v_and_b32_e32 v173, 0xffff0000, v132
	v_max_f32_e32 v130, 0xda24260, v130
	v_pk_mul_f32 v[170:171], v[170:171], v[172:173]
	v_rcp_f32_e32 v172, v130
	v_max_f32_e32 v130, v175, v175
	v_max_f32_e32 v132, v174, v174
	v_lshlrev_b32_e32 v174, 16, v131
	v_and_b32_e32 v175, 0xffff0000, v131
	v_max_f32_e32 v131, v176, v176
	v_max_f32_e32 v130, 0xda24260, v130
	v_max_f32_e32 v131, 0xda24260, v131
	v_rcp_f32_e32 v130, v130
	v_rcp_f32_e32 v131, v131
	v_max_f32_e32 v132, 0xda24260, v132
	v_rcp_f32_e32 v173, v132
	v_lshlrev_b32_e32 v132, 16, v133
	v_and_b32_e32 v133, 0xffff0000, v133
	v_pk_mul_f32 v[130:131], v[130:131], v[132:133]
	v_pk_mul_f32 v[118:119], v[118:119], v[158:159]
	v_pk_mul_f32 v[116:117], v[116:117], v[130:131]
	v_add_u32_e32 v130, 0x90, v168
	v_mad_i64_i32 v[158:159], s[58:59], v130, s78, v[156:157]
	v_pk_mul_f32 v[172:173], v[172:173], v[174:175]
	v_add_co_u32_e32 v174, vcc, s61, v158
	v_pk_mul_f32 v[120:121], v[120:121], v[172:173]
	s_nop 0
	v_addc_co_u32_e32 v175, vcc, 0, v159, vcc
	v_add_co_u32_e32 v158, vcc, s77, v158
	v_pk_mul_f32 v[114:115], v[114:115], v[170:171]
	s_nop 0
	v_addc_co_u32_e32 v159, vcc, 0, v159, vcc
	s_nop 0
	s_nop 0
	s_waitcnt vmcnt(9)
	v_mov_b32_e32 v130, v222
	v_mov_b32_e32 v131, v223
	v_mov_b32_e32 v132, v224
	v_mov_b32_e32 v133, v225
	global_load_dwordx4 v[222:225], v[230:231], off offset:256
	v_and_b32_e32 v177, 0xffff0000, v130
	s_waitcnt vmcnt(9)
	v_mov_b32_e32 v170, v226
	v_mov_b32_e32 v171, v227
	v_mov_b32_e32 v172, v228
	v_mov_b32_e32 v173, v229
	global_load_dwordx4 v[226:229], v[232:233], off offset:256
	v_lshlrev_b32_e32 v169, 16, v170
	v_max_f32_e32 v169, v169, v169
	v_lshlrev_b32_e32 v178, 16, v171
	v_and_b32_e32 v179, 0xffff0000, v171
	v_lshlrev_b32_e32 v171, 16, v172
	v_max_f32_e32 v169, 0xda24260, v169
	v_and_b32_e32 v176, 0xffff0000, v170
	v_rcp_f32_e32 v170, v169
	v_max_f32_e32 v169, v171, v171
	v_max_f32_e32 v169, 0xda24260, v169
	v_and_b32_e32 v180, 0xffff0000, v172
	v_rcp_f32_e32 v172, v169
	v_max_f32_e32 v169, v176, v176
	v_max_f32_e32 v169, 0xda24260, v169
	v_lshlrev_b32_e32 v176, 16, v130
	v_max_f32_e32 v130, v180, v180
	v_rcp_f32_e32 v171, v169
	v_max_f32_e32 v130, 0xda24260, v130
	v_lshlrev_b32_e32 v181, 16, v173
	v_and_b32_e32 v182, 0xffff0000, v173
	v_rcp_f32_e32 v173, v130
	v_max_f32_e32 v130, v178, v178
	v_pk_mul_f32 v[170:171], v[170:171], v[176:177]
	v_lshlrev_b32_e32 v176, 16, v132
	v_and_b32_e32 v177, 0xffff0000, v132
	v_max_f32_e32 v130, 0xda24260, v130
	v_pk_mul_f32 v[172:173], v[172:173], v[176:177]
	v_rcp_f32_e32 v176, v130
	v_max_f32_e32 v130, v181, v181
	v_lshlrev_b32_e32 v180, 16, v131
	v_and_b32_e32 v181, 0xffff0000, v131
	v_max_f32_e32 v131, v182, v182
	v_max_f32_e32 v130, 0xda24260, v130
	v_max_f32_e32 v131, 0xda24260, v131
	v_rcp_f32_e32 v130, v130
	v_rcp_f32_e32 v131, v131
	v_max_f32_e32 v132, v179, v179
	v_max_f32_e32 v132, 0xda24260, v132
	v_rcp_f32_e32 v177, v132
	v_lshlrev_b32_e32 v132, 16, v133
	v_and_b32_e32 v133, 0xffff0000, v133
	v_pk_mul_f32 v[130:131], v[130:131], v[132:133]
	v_pk_mul_f32 v[102:103], v[102:103], v[170:171]
	v_pk_mul_f32 v[100:101], v[100:101], v[130:131]
	v_pk_mul_f32 v[98:99], v[98:99], v[172:173]
	s_nop 0
	s_nop 0
	v_pk_mul_f32 v[176:177], v[176:177], v[180:181]
	s_waitcnt vmcnt(9)
	v_mov_b32_e32 v130, v184
	v_mov_b32_e32 v131, v185
	v_mov_b32_e32 v132, v186
	v_mov_b32_e32 v133, v187
	s_waitcnt vmcnt(8)
	v_mov_b32_e32 v170, v188
	v_mov_b32_e32 v171, v189
	v_mov_b32_e32 v172, v190
	v_mov_b32_e32 v173, v191
	v_lshlrev_b32_e32 v158, 16, v170
	v_and_b32_e32 v159, 0xffff0000, v170
	v_lshlrev_b32_e32 v169, 16, v171
	v_and_b32_e32 v174, 0xffff0000, v171
	v_lshlrev_b32_e32 v170, 16, v172
	v_and_b32_e32 v171, 0xffff0000, v172
	v_max_f32_e32 v158, v158, v158
	v_max_f32_e32 v159, v159, v159
	v_pk_mul_f32 v[104:105], v[104:105], v[176:177]
	v_lshlrev_b32_e32 v175, 16, v173
	v_and_b32_e32 v176, 0xffff0000, v173
	v_max_f32_e32 v158, 0xda24260, v158
	v_max_f32_e32 v170, v170, v170
	v_max_f32_e32 v159, 0xda24260, v159
	v_lshlrev_b32_e32 v172, 16, v130
	v_and_b32_e32 v173, 0xffff0000, v130
	v_max_f32_e32 v130, v171, v171
	v_rcp_f32_e32 v158, v158
	v_max_f32_e32 v170, 0xda24260, v170
	v_rcp_f32_e32 v159, v159
	v_max_f32_e32 v130, 0xda24260, v130
	v_rcp_f32_e32 v170, v170
	v_rcp_f32_e32 v171, v130
	v_max_f32_e32 v130, v169, v169
	v_pk_mul_f32 v[158:159], v[158:159], v[172:173]
	v_lshlrev_b32_e32 v172, 16, v132
	v_and_b32_e32 v173, 0xffff0000, v132
	v_max_f32_e32 v130, 0xda24260, v130
	v_pk_mul_f32 v[170:171], v[170:171], v[172:173]
	v_rcp_f32_e32 v172, v130
	v_max_f32_e32 v130, v175, v175
	v_max_f32_e32 v132, v174, v174
	v_lshlrev_b32_e32 v174, 16, v131
	v_and_b32_e32 v175, 0xffff0000, v131
	v_max_f32_e32 v131, v176, v176
	v_max_f32_e32 v130, 0xda24260, v130
	v_max_f32_e32 v131, 0xda24260, v131
	v_rcp_f32_e32 v130, v130
	v_rcp_f32_e32 v131, v131
	v_max_f32_e32 v132, 0xda24260, v132
	v_rcp_f32_e32 v173, v132
	v_lshlrev_b32_e32 v132, 16, v133
	v_and_b32_e32 v133, 0xffff0000, v133
	v_pk_mul_f32 v[130:131], v[130:131], v[132:133]
	v_pk_mul_f32 v[78:79], v[78:79], v[158:159]
	v_pk_mul_f32 v[76:77], v[76:77], v[130:131]
	v_add_u32_e32 v130, 0xa0, v168
	v_mad_i64_i32 v[158:159], s[58:59], v130, s78, v[156:157]
	v_pk_mul_f32 v[172:173], v[172:173], v[174:175]
	v_add_co_u32_e32 v174, vcc, s61, v158
	v_pk_mul_f32 v[80:81], v[80:81], v[172:173]
	s_nop 0
	v_addc_co_u32_e32 v175, vcc, 0, v159, vcc
	v_add_co_u32_e32 v158, vcc, s77, v158
	v_pk_mul_f32 v[74:75], v[74:75], v[170:171]
	s_nop 0
	v_addc_co_u32_e32 v159, vcc, 0, v159, vcc
	s_nop 0
	s_nop 0
	s_waitcnt vmcnt(7)
; __device__ __forceinline__ float bflo(unsigned w) { return __uint_as_float(w << 16); }
; __device__ __forceinline__ float bfhi(unsigned w) { return __uint_as_float(w & 0xffff0000u); }
;     __device__ __forceinline__ void mid(f32x4 (&acc)[2][2][4][2], const Unit& u, int wr, int wc, int fr, int fq) const {
;     ...
;             for (int m = 0; m < 4; ++m) { const bf16_t* pr = P + (size_t)(row0 + ai * HALF + m * 16) * NP + col0;
; #pragma unroll
;                 for (int bj = 0; bj < 2; ++bj) { const u32x4 a = *(const u32x4*)(pr + PC_GA + bj * HALF), b = *(const u32x4*)(pr + PC_GB + bj * HALF);
;                     const f32x4 b0 = {bflo(b.x), bfhi(b.x), bflo(b.y), bfhi(b.y)}, b1 = {bflo(b.z), bfhi(b.z), bflo(b.w), bfhi(b.w)};
;                     const f32x4 a0 = {bflo(a.x), bfhi(a.x), bflo(a.y), bfhi(a.y)}, a1 = {bflo(a.z), bfhi(a.z), bflo(a.w), bfhi(a.w)};
;                     f32x4 r0, r1;
; #pragma unroll
;                     for (int j = 0; j < 4; ++j) { r0[j] = a0[j] * __builtin_amdgcn_rcpf(fmaxf(b0[j], 1e-30f)); r1[j] = a1[j] * __builtin_amdgcn_rcpf(fmaxf(b1[j], 1e-30f)); }
;                     acc[ai][bj][m][0] *= r0; acc[ai][bj][m][1] *= r1; }
	v_mov_b32_e32 v130, v198
	v_mov_b32_e32 v131, v199
	v_mov_b32_e32 v132, v200
	v_mov_b32_e32 v133, v201
	v_and_b32_e32 v177, 0xffff0000, v130
	s_waitcnt vmcnt(6)
	v_mov_b32_e32 v170, v202
	v_mov_b32_e32 v171, v203
	v_mov_b32_e32 v172, v204
	v_mov_b32_e32 v173, v205
	v_lshlrev_b32_e32 v169, 16, v170
	v_max_f32_e32 v169, v169, v169
	v_lshlrev_b32_e32 v178, 16, v171
	v_and_b32_e32 v179, 0xffff0000, v171
	v_lshlrev_b32_e32 v171, 16, v172
	v_max_f32_e32 v169, 0xda24260, v169
	v_and_b32_e32 v176, 0xffff0000, v170
	v_rcp_f32_e32 v170, v169
	v_max_f32_e32 v169, v171, v171
	v_max_f32_e32 v169, 0xda24260, v169
	v_and_b32_e32 v180, 0xffff0000, v172
	v_rcp_f32_e32 v172, v169
	v_max_f32_e32 v169, v176, v176
	v_max_f32_e32 v169, 0xda24260, v169
	v_lshlrev_b32_e32 v176, 16, v130
	v_max_f32_e32 v130, v180, v180
	v_rcp_f32_e32 v171, v169
	v_max_f32_e32 v130, 0xda24260, v130
	v_lshlrev_b32_e32 v181, 16, v173
	v_and_b32_e32 v182, 0xffff0000, v173
	v_rcp_f32_e32 v173, v130
	v_max_f32_e32 v130, v178, v178
	v_pk_mul_f32 v[170:171], v[170:171], v[176:177]
	v_lshlrev_b32_e32 v176, 16, v132
	v_and_b32_e32 v177, 0xffff0000, v132
	v_max_f32_e32 v130, 0xda24260, v130
	v_pk_mul_f32 v[172:173], v[172:173], v[176:177]
	v_rcp_f32_e32 v176, v130
	v_max_f32_e32 v130, v181, v181
	v_lshlrev_b32_e32 v180, 16, v131
	v_and_b32_e32 v181, 0xffff0000, v131
	v_max_f32_e32 v131, v182, v182
	v_max_f32_e32 v130, 0xda24260, v130
	v_max_f32_e32 v131, 0xda24260, v131
	v_rcp_f32_e32 v130, v130
	v_rcp_f32_e32 v131, v131
	v_max_f32_e32 v132, v179, v179
	v_max_f32_e32 v132, 0xda24260, v132
	v_rcp_f32_e32 v177, v132
	v_lshlrev_b32_e32 v132, 16, v133
	v_and_b32_e32 v133, 0xffff0000, v133
	v_pk_mul_f32 v[130:131], v[130:131], v[132:133]
	v_pk_mul_f32 v[62:63], v[62:63], v[170:171]
	v_pk_mul_f32 v[60:61], v[60:61], v[130:131]
	v_pk_mul_f32 v[58:59], v[58:59], v[172:173]
	s_nop 0
	s_nop 0
	v_pk_mul_f32 v[176:177], v[176:177], v[180:181]
	s_waitcnt vmcnt(5)
	v_mov_b32_e32 v130, v206
	v_mov_b32_e32 v131, v207
	v_mov_b32_e32 v132, v208
	v_mov_b32_e32 v133, v209
	s_waitcnt vmcnt(4)
	v_mov_b32_e32 v170, v210
	v_mov_b32_e32 v171, v211
	v_mov_b32_e32 v172, v212
	v_mov_b32_e32 v173, v213
	v_lshlrev_b32_e32 v158, 16, v170
	v_and_b32_e32 v159, 0xffff0000, v170
	v_lshlrev_b32_e32 v169, 16, v171
	v_and_b32_e32 v174, 0xffff0000, v171
	v_lshlrev_b32_e32 v170, 16, v172
	v_and_b32_e32 v171, 0xffff0000, v172
	v_max_f32_e32 v158, v158, v158
	v_max_f32_e32 v159, v159, v159
	v_pk_mul_f32 v[64:65], v[64:65], v[176:177]
	v_lshlrev_b32_e32 v175, 16, v173
	v_and_b32_e32 v176, 0xffff0000, v173
	v_max_f32_e32 v158, 0xda24260, v158
	v_max_f32_e32 v170, v170, v170
	v_max_f32_e32 v159, 0xda24260, v159
	v_lshlrev_b32_e32 v172, 16, v130
	v_and_b32_e32 v173, 0xffff0000, v130
	v_max_f32_e32 v130, v171, v171
	v_rcp_f32_e32 v158, v158
	v_max_f32_e32 v170, 0xda24260, v170
	v_rcp_f32_e32 v159, v159
	v_max_f32_e32 v130, 0xda24260, v130
	v_rcp_f32_e32 v170, v170
	v_rcp_f32_e32 v171, v130
	v_max_f32_e32 v130, v169, v169
	v_pk_mul_f32 v[158:159], v[158:159], v[172:173]
	v_lshlrev_b32_e32 v172, 16, v132
	v_and_b32_e32 v173, 0xffff0000, v132
	v_max_f32_e32 v130, 0xda24260, v130
	v_pk_mul_f32 v[170:171], v[170:171], v[172:173]
	v_rcp_f32_e32 v172, v130
	v_max_f32_e32 v130, v175, v175
	v_max_f32_e32 v132, v174, v174
	v_lshlrev_b32_e32 v174, 16, v131
	v_and_b32_e32 v175, 0xffff0000, v131
	v_max_f32_e32 v131, v176, v176
	v_max_f32_e32 v130, 0xda24260, v130
	v_max_f32_e32 v131, 0xda24260, v131
	v_rcp_f32_e32 v130, v130
	v_rcp_f32_e32 v131, v131
	v_max_f32_e32 v132, 0xda24260, v132
	v_rcp_f32_e32 v173, v132
	v_lshlrev_b32_e32 v132, 16, v133
	v_and_b32_e32 v133, 0xffff0000, v133
	v_pk_mul_f32 v[130:131], v[130:131], v[132:133]
	v_pk_mul_f32 v[46:47], v[46:47], v[158:159]
	v_pk_mul_f32 v[44:45], v[44:45], v[130:131]
	v_add_u32_e32 v130, 0xb0, v168
	v_mad_i64_i32 v[156:157], s[58:59], v130, s78, v[156:157]
	v_add_co_u32_e32 v158, vcc, s61, v156
	v_pk_mul_f32 v[42:43], v[42:43], v[170:171]
	s_nop 0
	v_addc_co_u32_e32 v159, vcc, 0, v157, vcc
	v_add_co_u32_e32 v156, vcc, s77, v156
	s_nop 0
	s_nop 0
	v_addc_co_u32_e32 v157, vcc, 0, v157, vcc
	s_nop 0
	v_pk_mul_f32 v[172:173], v[172:173], v[174:175]
	s_waitcnt vmcnt(3)
; __device__ __forceinline__ float bflo(unsigned w) { return __uint_as_float(w << 16); }
; __device__ __forceinline__ float bfhi(unsigned w) { return __uint_as_float(w & 0xffff0000u); }
;     __device__ __forceinline__ void mid(f32x4 (&acc)[2][2][4][2], const Unit& u, int wr, int wc, int fr, int fq) const {
;     ...
;             for (int m = 0; m < 4; ++m) { const bf16_t* pr = P + (size_t)(row0 + ai * HALF + m * 16) * NP + col0;
; #pragma unroll
;                 for (int bj = 0; bj < 2; ++bj) { const u32x4 a = *(const u32x4*)(pr + PC_GA + bj * HALF), b = *(const u32x4*)(pr + PC_GB + bj * HALF);
;                     const f32x4 b0 = {bflo(b.x), bfhi(b.x), bflo(b.y), bfhi(b.y)}, b1 = {bflo(b.z), bfhi(b.z), bflo(b.w), bfhi(b.w)};
;                     const f32x4 a0 = {bflo(a.x), bfhi(a.x), bflo(a.y), bfhi(a.y)}, a1 = {bflo(a.z), bfhi(a.z), bflo(a.w), bfhi(a.w)};
;                     f32x4 r0, r1;
; #pragma unroll
;                     for (int j = 0; j < 4; ++j) { r0[j] = a0[j] * __builtin_amdgcn_rcpf(fmaxf(b0[j], 1e-30f)); r1[j] = a1[j] * __builtin_amdgcn_rcpf(fmaxf(b1[j], 1e-30f)); }
;                     acc[ai][bj][m][0] *= r0; acc[ai][bj][m][1] *= r1; }
	v_mov_b32_e32 v130, v214
	v_mov_b32_e32 v131, v215
	v_mov_b32_e32 v132, v216
	v_mov_b32_e32 v133, v217
	s_waitcnt vmcnt(2)
	v_mov_b32_e32 v168, v218
	v_mov_b32_e32 v169, v219
	v_mov_b32_e32 v170, v220
	v_mov_b32_e32 v171, v221
	v_lshlrev_b32_e32 v174, 16, v169
	v_and_b32_e32 v175, 0xffff0000, v169
	v_lshlrev_b32_e32 v169, 16, v170
	v_max_f32_e32 v169, v169, v169
	v_pk_mul_f32 v[48:49], v[48:49], v[172:173]
	v_lshlrev_b32_e32 v172, 16, v168
	v_and_b32_e32 v173, 0xffff0000, v168
	v_max_f32_e32 v169, 0xda24260, v169
	v_and_b32_e32 v176, 0xffff0000, v170
	v_max_f32_e32 v168, v172, v172
	v_rcp_f32_e32 v170, v169
	v_max_f32_e32 v169, v173, v173
	v_max_f32_e32 v168, 0xda24260, v168
	v_max_f32_e32 v169, 0xda24260, v169
	v_lshlrev_b32_e32 v172, 16, v130
	v_and_b32_e32 v173, 0xffff0000, v130
	v_max_f32_e32 v130, v176, v176
	v_rcp_f32_e32 v168, v168
	v_rcp_f32_e32 v169, v169
	v_max_f32_e32 v130, 0xda24260, v130
	v_lshlrev_b32_e32 v177, 16, v171
	v_and_b32_e32 v178, 0xffff0000, v171
	v_rcp_f32_e32 v171, v130
	v_max_f32_e32 v130, v174, v174
	v_pk_mul_f32 v[168:169], v[168:169], v[172:173]
	v_lshlrev_b32_e32 v172, 16, v132
	v_and_b32_e32 v173, 0xffff0000, v132
	v_max_f32_e32 v130, 0xda24260, v130
	v_pk_mul_f32 v[170:171], v[170:171], v[172:173]
	v_rcp_f32_e32 v172, v130
	v_max_f32_e32 v130, v177, v177
	v_max_f32_e32 v132, v175, v175
	v_lshlrev_b32_e32 v174, 16, v131
	v_and_b32_e32 v175, 0xffff0000, v131
	v_max_f32_e32 v131, v178, v178
	v_max_f32_e32 v130, 0xda24260, v130
	v_max_f32_e32 v131, 0xda24260, v131
	v_rcp_f32_e32 v130, v130
	v_rcp_f32_e32 v131, v131
	v_max_f32_e32 v132, 0xda24260, v132
	v_rcp_f32_e32 v173, v132
	v_lshlrev_b32_e32 v132, 16, v133
	v_and_b32_e32 v133, 0xffff0000, v133
	v_pk_mul_f32 v[130:131], v[130:131], v[132:133]
	v_pk_mul_f32 v[18:19], v[18:19], v[170:171]
	v_pk_mul_f32 v[20:21], v[20:21], v[130:131]
	s_nop 0
	s_nop 0
	s_nop 0
	v_pk_mul_f32 v[172:173], v[172:173], v[174:175]
	v_pk_mul_f32 v[22:23], v[22:23], v[168:169]
	v_pk_mul_f32 v[24:25], v[24:25], v[172:173]
	s_waitcnt vmcnt(1)
	v_mov_b32_e32 v130, v222
	v_mov_b32_e32 v131, v223
	v_mov_b32_e32 v132, v224
	v_mov_b32_e32 v133, v225
	s_waitcnt vmcnt(0)
	v_mov_b32_e32 v156, v226
	v_mov_b32_e32 v157, v227
	v_mov_b32_e32 v158, v228
	v_mov_b32_e32 v159, v229
	v_lshlrev_b32_e32 v170, 16, v157
	v_and_b32_e32 v171, 0xffff0000, v157
	v_lshlrev_b32_e32 v157, 16, v158
	v_max_f32_e32 v157, v157, v157
	v_lshlrev_b32_e32 v168, 16, v156
	v_and_b32_e32 v169, 0xffff0000, v156
	v_max_f32_e32 v157, 0xda24260, v157
	v_and_b32_e32 v172, 0xffff0000, v158
	v_max_f32_e32 v156, v168, v168
	v_rcp_f32_e32 v158, v157
	v_max_f32_e32 v157, v169, v169
	v_max_f32_e32 v156, 0xda24260, v156
	v_max_f32_e32 v157, 0xda24260, v157
	v_lshlrev_b32_e32 v168, 16, v130
	v_and_b32_e32 v169, 0xffff0000, v130
	v_max_f32_e32 v130, v172, v172
	v_rcp_f32_e32 v156, v156
	v_rcp_f32_e32 v157, v157
	v_max_f32_e32 v130, 0xda24260, v130
	v_lshlrev_b32_e32 v173, 16, v159
	v_and_b32_e32 v174, 0xffff0000, v159
	v_rcp_f32_e32 v159, v130
	v_max_f32_e32 v130, v170, v170
	v_pk_mul_f32 v[156:157], v[156:157], v[168:169]
	v_lshlrev_b32_e32 v168, 16, v132
	v_and_b32_e32 v169, 0xffff0000, v132
	v_max_f32_e32 v130, 0xda24260, v130
	v_pk_mul_f32 v[158:159], v[158:159], v[168:169]
	v_rcp_f32_e32 v168, v130
	v_max_f32_e32 v130, v173, v173
	v_max_f32_e32 v132, v171, v171
	v_lshlrev_b32_e32 v170, 16, v131
	v_and_b32_e32 v171, 0xffff0000, v131
	v_max_f32_e32 v131, v174, v174
	v_max_f32_e32 v130, 0xda24260, v130
	v_max_f32_e32 v132, 0xda24260, v132
	v_max_f32_e32 v131, 0xda24260, v131
	v_rcp_f32_e32 v130, v130
	v_rcp_f32_e32 v169, v132
	v_rcp_f32_e32 v131, v131
	v_lshlrev_b32_e32 v132, 16, v133
	v_and_b32_e32 v133, 0xffff0000, v133
	v_pk_mul_f32 v[168:169], v[168:169], v[170:171]
	v_pk_mul_f32 v[130:131], v[130:131], v[132:133]
	v_pk_mul_f32 v[8:9], v[8:9], v[168:169]
	v_pk_mul_f32 v[6:7], v[6:7], v[156:157]
	v_pk_mul_f32 v[4:5], v[4:5], v[130:131]
	v_pk_mul_f32 v[2:3], v[2:3], v[158:159]
